# attention: f32 bias table loaded into the QK accumulators (no bias MFMAs); half-step-1 softmax-finish VALU woven into the QK MFMA shadows (K fragment temps moved to freed registers)
# speedup vs baseline: 1.0028x; 1.0028x over previous
; #define VMW() asm volatile("s_waitcnt vmcnt(0)" ::: "memory")
; __device__ __forceinline__ void fill_cb(const float* C, int P0, char* cb) {
;     const int n = P0 + QB; const float ref = C[P0];
;     for (int i = threadIdx.x * 4; i < n; i += 2048) { const f32x4 c = *(const f32x4*)(C + i); u32x4 o0, o1;
; #pragma unroll
;         for (int j = 0; j < 4; ++j) { const float x = (ref - c[j]) * INV_SCALE; const unsigned u1 = __float_as_uint(x) & 0xffff0000u; const float r1 = x - __uint_as_float(u1);
;             const unsigned u2 = __float_as_uint(r1) & 0xffff0000u; const float r2 = r1 - __uint_as_float(u2); const unsigned u3 = cvtpk(r2, 0.f) & 0xffffu;
;             const unsigned w0 = (u1 >> 16) | u2, w1 = u3;
;             if (j < 2) { o0[2 * j] = w0; o0[2 * j + 1] = w1; } else { o1[2 * (j - 2)] = w0; o1[2 * (j - 2) + 1] = w1; } }
;         *(u32x4*)(cb + (size_t)i * 8) = o0; *(u32x4*)(cb + (size_t)i * 8 + 16) = o1; }
; }
; __device__ __forceinline__ void fox_prime(const BlockRef& cur, char* lds, char* cbcur, Seam& S) {
;     const int tid = threadIdx.x, wid = __builtin_amdgcn_readfirstlane(tid >> 6), lane = tid & 63, r32 = lane & 31, hi = lane >> 5;
;     const int sr = tid >> 4, sc = (tid & 15) * 8; char* K_lds = lds + 2 * SHM_V;
;     for (int d0 = 0; d0 < 8; ++d0) S.qr[d0] = load8(cur.Q + (size_t)(wid * QBLK + r32) * QP + d0 * 16 + hi * 8);
;     SLOAD_H(cur.K, cur.V, cur.P0 + QB - KVBLK); VMW(); SWRITE_HK(0);
;     fill_cb(cur.C, cur.P0, cbcur);
;     __syncthreads();
; }
; __device__ __forceinline__ void fox_block(const BlockRef& cur, const BlockRef& nxt, char* lds, char* cbcur, char* cbnxt, Seam& S) {
;     const int tid = threadIdx.x, wid = __builtin_amdgcn_readfirstlane(tid >> 6), lane = tid & 63, r32 = lane & 31, hi = lane >> 5;
;     const int W = 1 << 30;
;     const int NT = (cur.P0 + QB) / KVBLK;
;     const int qlo = cur.P0 + wid * QBLK, qm = qlo + r32 - 4 * hi;
;     char* V_lds = lds; char* K_lds = lds + 2 * SHM_V;
;     float* ws = (float*)(lds + LDS_WS_OFF) + wid * 64; float* li_l = ws, * al_l = ws + 32;
;     float m_reg = -1e30f, l_reg = 0; f32x16 o[4] = {};
;     const int sr = tid >> 4, sc = (tid & 15) * 8;
;     const int vb0 = (int)(uintptr_t)V_lds + v_rd_base(lane);
;     const bf16* Kh = cur.K; const bf16* Vh = cur.V;
;     const char* cbl = cbcur + 8 * r32;
.Lattn_entry:
	s_cmpk_gt_i32 s86, 0x1ff
	s_cbranch_scc1 .LBB0_263
	s_ashr_i32 s4, s86, 6
	s_ashr_i32 s5, s4, 31
	s_lshl_b32 s13, s86, 8
	s_lshl_b64 s[6:7], s[4:5], 12
	s_and_b32 s84, s13, 0x700
	s_or_b32 s6, s6, s84
	s_ashr_i32 s12, s86, 3
	s_lshl_b64 s[14:15], s[6:7], 12
	s_add_u32 s13, s40, s14
	s_addc_u32 s15, s41, s15
	s_lshl_b32 s14, s12, 7
	s_and_b32 s14, s14, 0x380
	s_lshl_b32 s18, s14, 1
	s_add_u32 s14, s13, s18
	s_addc_u32 s15, s15, 0
	s_lshl_b64 s[16:17], s[4:5], 23
	s_add_u32 s4, s34, s16
	s_addc_u32 s5, s35, s17
	s_add_u32 s4, s4, s18
	s_addc_u32 s5, s5, 0
	s_add_u32 s13, s54, s16
	s_addc_u32 s16, s55, s17
	s_add_u32 s74, s13, s18
	s_addc_u32 s75, s16, 0
	s_ashr_i32 s13, s12, 31
	s_lshl_b64 s[12:13], s[12:13], 14
	s_add_u32 s12, s58, s12
	v_readfirstlane_b32 s16, v0
	s_addc_u32 s13, s59, s13
	s_lshr_b32 s16, s16, 1
	v_and_b32_e32 v1, 31, v0
	s_and_b32 s16, s16, 0x7fffffe0
	v_or_b32_e32 v4, s16, v1
	v_mov_b32_e32 v5, 0
	v_lshlrev_b64 v[2:3], 12, v[4:5]
	v_lshrrev_b32_e32 v4, 1, v0
	v_lshl_add_u64 v[2:3], s[14:15], 0, v[2:3]
	v_and_b32_e32 v4, 16, v4
	v_lshl_add_u64 v[2:3], v[2:3], 0, v[4:5]
	global_load_dwordx4 v[158:161], v[2:3], off offset:2048
	global_load_dwordx4 v[154:157], v[2:3], off offset:2080
	global_load_dwordx4 v[150:153], v[2:3], off offset:2112
	global_load_dwordx4 v[146:149], v[2:3], off offset:2144
	global_load_dwordx4 v[142:145], v[2:3], off offset:2176
	global_load_dwordx4 v[138:141], v[2:3], off offset:2208
	global_load_dwordx4 v[134:137], v[2:3], off offset:2240
	global_load_dwordx4 v[130:133], v[2:3], off offset:2272
	v_lshrrev_b32_e32 v192, 4, v0
	v_or_b32_e32 v4, 0xc0, v192
	v_lshlrev_b32_e32 v2, 3, v0
	v_or_b32_e32 v4, s84, v4
	v_and_b32_e32 v3, 0x78, v2
	v_lshlrev_b32_e32 v4, 11, v4
	v_or_b32_e32 v193, 0xe0, v192
	v_lshl_add_u64 v[6:7], s[74:75], 0, v[4:5]
	v_lshlrev_b32_e32 v182, 1, v3
	v_mov_b32_e32 v183, v5
	v_or_b32_e32 v3, s84, v193
	v_lshl_add_u64 v[12:13], v[6:7], 0, v[182:183]
	v_lshlrev_b32_e32 v6, 11, v3
	v_mov_b32_e32 v7, v5
	v_lshl_add_u64 v[8:9], s[74:75], 0, v[6:7]
	v_lshl_add_u64 v[4:5], s[4:5], 0, v[4:5]
	v_lshl_add_u64 v[6:7], s[4:5], 0, v[6:7]
	v_lshl_add_u64 v[14:15], v[8:9], 0, v[182:183]
	v_lshl_add_u64 v[4:5], v[4:5], 0, v[182:183]
	v_lshl_add_u64 v[8:9], v[6:7], 0, v[182:183]
	global_load_dwordx4 v[4:7], v[4:5], off
	s_nop 0
	global_load_dwordx4 v[8:11], v[8:9], off
	s_nop 0
	global_load_dwordx4 v[102:105], v[12:13], off
	global_load_dwordx4 v[98:101], v[14:15], off
	v_mov_b32_e32 v3, v0
	s_waitcnt vmcnt(0)
	s_movk_i32 s16, 0xf0
	v_lshlrev_b32_e32 v12, 4, v3
	v_and_b32_e32 v3, 0x70, v3
	v_lshlrev_b32_e32 v239, 2, v0
	s_add_i32 s17, s84, 0x100
	v_and_b32_e32 v13, 0xffffff00, v12
	v_bitop3_b32 v3, v12, v3, s16 bitop3:0x6c
	v_add3_u32 v3, 0, v13, v3
	v_cmp_le_u32_e32 vcc, s17, v239
	s_waitcnt vmcnt(0)
	ds_write_b128 v3, v[4:7] offset:32768
	ds_write_b128 v3, v[8:11] offset:40960
	s_and_saveexec_b64 s[16:17], vcc
	s_xor_b64 s[16:17], exec, s[16:17]
	v_lshlrev_b32_e32 v3, 5, v0
	s_andn2_saveexec_b64 s[16:17], s[16:17]
	s_cbranch_execz .LBB0_223
	s_lshl_b32 s19, s84, 2
	v_mov_b32_e32 v3, s19
	v_lshlrev_b32_e32 v4, 2, v239
	global_load_dword v8, v3, s[12:13]
	s_nop 0
	global_load_dwordx4 v[4:7], v4, s[12:13]
	v_lshlrev_b32_e32 v3, 5, v0
	v_add_u32_e32 v10, 0, v3
	v_lshlrev_b32_e32 v12, 4, v0
	v_add_u32_e32 v12, 0x10800, v12
	s_mov_b32 s19, 0x413504f3
	v_mov_b32_e32 v9, 0
	s_waitcnt vmcnt(0)
	v_sub_f32_e32 v4, v8, v4
	v_sub_f32_e32 v5, v8, v5
	v_sub_f32_e32 v6, v8, v6
	v_sub_f32_e32 v7, v8, v7
	v_mul_f32_e32 v8, 0x413504f3, v4
	v_mul_f32_e32 v10, 0x413504f3, v5
	v_mul_f32_e32 v11, 0x413504f3, v6
	v_mul_f32_e32 v13, 0x413504f3, v7
	v_mov_b32_e32 v4, v8
	v_mov_b32_e32 v5, v10
	v_mov_b32_e32 v6, v11
	v_mov_b32_e32 v7, v13
	ds_write_b128 v12, v[4:7]
.LBB0_223:
	s_or_b64 exec, exec, s[16:17]
	s_add_u32 s70, s14, 0x800
	s_addc_u32 s71, s15, 0
	s_lshl_b64 s[6:7], s[6:7], 11
	s_add_u32 s6, s56, s6
	s_addc_u32 s7, s57, s7
	s_add_u32 s72, s6, s18
	s_addc_u32 s73, s7, 0
	v_lshlrev_b32_e32 v184, 4, v0
	v_lshlrev_b32_e32 v6, 1, v0
	v_and_b32_e32 v5, 0xc0, v184
	v_and_b32_e32 v6, 32, v6
	v_and_b32_e32 v2, 0x118, v2
	s_cmp_lg_u32 0, -1
	v_or3_b32 v2, v6, v5, v2
	s_cselect_b32 s6, 0, 0
	v_and_b32_e32 v201, 63, v0
	v_add_u32_e32 v199, s6, v2
	v_lshlrev_b32_e32 v5, 3, v1
	s_add_i32 s6, 0, 0x10800
	v_bfe_u32 v200, v0, 5, 1
	v_lshlrev_b32_e32 v200, 4, v200
	v_add_u32_e32 v200, s6, v200
	v_mov_b32_e32 v2, 0x3f803f80
	v_cmp_gt_u32_e64 s[6:7], 32, v201
	v_bfe_u32 v4, v0, 5, 1
	v_and_b32_e32 v7, 0x70, v184
	v_cndmask_b32_e64 v162, 0, v2, s[6:7]
	v_mov_b32_e32 v2, 0x3f80
	v_cndmask_b32_e64 v163, 0, v2, s[6:7]
	v_lshlrev_b32_e32 v2, 4, v4
	v_xad_u32 v8, v2, v7, 0
	v_or_b32_e32 v9, 32, v2
	v_or_b32_e32 v10, 64, v2
	v_or_b32_e32 v2, 0x60, v2
	v_lshlrev_b32_e32 v203, 2, v4
	v_mov_b32_e32 v183, 0
	v_lshlrev_b32_e32 v6, 8, v1
	v_xad_u32 v9, v9, v7, 0
	v_xad_u32 v10, v10, v7, 0
	v_xad_u32 v7, v2, v7, 0
	v_lshlrev_b32_e32 v2, 3, v4
	v_add_u32_e32 v4, 0, v5
	v_add_u32_e32 v3, 0, v3
	s_mov_b32 s15, 0
	v_sub_u32_e32 v198, v1, v203
	v_mov_b32_e32 v164, v183
	v_mov_b32_e32 v165, v183
	v_add_u32_e32 v202, 0xfffffd00, v200
	v_add_u32_e32 v204, 0x10810, v3
	v_mov_b32_e32 v185, v183
	s_brev_b32 s17, -3
	s_mov_b32 s78, 0x41000000
	s_mov_b32 s16, 0x3e0293ee
	s_movk_i32 s79, 0xf0
	v_lshlrev_b32_e32 v186, 1, v2
	s_movk_i32 s80, 0x110
	s_mov_b32 s81, 0x413504f3
	s_mov_b64 s[18:19], 0x2000
	v_add_u32_e32 v205, v8, v6
	v_add_u32_e32 v206, v9, v6
	v_add_u32_e32 v207, v10, v6
	v_add_u32_e32 v208, v7, v6
	v_mov_b32_e32 v209, 0xff800000
	v_mov_b32_e32 v210, 0xf149f2ca
	s_mov_b64 s[20:21], s[70:71]
	s_mov_b32 s82, 0
	s_mov_b32 s83, s86
	s_mov_b64 s[64:65], s[72:73]
	s_mov_b64 s[62:63], s[74:75]
	s_mov_b64 s[22:23], s[4:5]
	s_waitcnt lgkmcnt(0)
	s_barrier
	s_branch .LBB0_225

; #define SBAR() __builtin_amdgcn_sched_barrier(0)
; #define SLOAD_H(Kp, Vp, k0) do { S.st_v0 = load8(ROWK(Vp, k0, sr)); S.st_v1 = load8(ROWK(Vp, k0, 32 + sr));              \
;                          S.st_k0 = load8(ROWK(Kp, k0, sr)); S.st_k1 = load8(ROWK(Kp, k0, 32 + sr)); } while (0)
; #define SWRITE_HV(bf) do { OPQ_TID(); const int vst0_ = v_st(sr_, sc_), vst1_ = v_st(32 + sr_, sc_); *(bf16x8*)(V_lds + (bf) * SHM_V + vst0_) = S.st_v0; *(bf16x8*)(V_lds + (bf) * SHM_V + vst1_) = S.st_v1; } while (0)
; template <int KB>
; __device__ __forceinline__ void qkt(f32x16& p0, f32x16& p1, const char* K_lds, const char* cbt, int r32, int hi, const bf16x8* qr) {
;     { const u32x2 e0 = *(const u32x2*)(cbt), e1 = *(const u32x2*)(cbt + 32 * 8);
;       const unsigned c0 = hi ? 0u : 0x3F803F80u, c1 = hi ? 0u : 0x00003F80u;
;       const u32x4 k0 = {e0.x, e0.y, e0.x, e0.y}, k1 = {e1.x, e1.y, e1.x, e1.y}, q1 = {c0, c1, 0u, 0u};
;       p0 = __builtin_amdgcn_mfma_f32_32x32x16_bf16(__builtin_bit_cast(bf16x8, k0), __builtin_bit_cast(bf16x8, q1), f32x16{}, 0, 0, 0);
;       p1 = __builtin_amdgcn_mfma_f32_32x32x16_bf16(__builtin_bit_cast(bf16x8, k1), __builtin_bit_cast(bf16x8, q1), f32x16{}, 0, 0, 0); }
;     const char* kb[4];
; #pragma unroll
;     for (int dd = 0; dd < 4; ++dd) kb[dd] = K_lds + KB * SHM_K + KSWZ(r32, (dd * 16 + hi * 8) * 2);
; #pragma unroll
;     for (int d0 = 0; d0 < 8; ++d0) { const char* a = kb[d0 & 3] + (d0 >> 2) * 128;
;         bf16x8 b0 = *reinterpret_cast<const bf16x8*>(a);
;         bf16x8 b1 = *reinterpret_cast<const bf16x8*>(a + 32 * 256);
;         p0 = __builtin_amdgcn_mfma_f32_32x32x16_bf16(b0, qr[d0], p0, 0, 0, 0);
;         p1 = __builtin_amdgcn_mfma_f32_32x32x16_bf16(b1, qr[d0], p1, 0, 0, 0); }
; }
; __device__ __forceinline__ void fox_block(const BlockRef& cur, const BlockRef& nxt, char* lds, char* cbcur, char* cbnxt, Seam& S) {
;     ...
;     SWRITE_HV(0); SBAR();
;     if (NT > 1) { SLOAD_H(Kh, Vh, KBASE(1)); }
;     SBAR(); qkt<0>(pA0, pA1, K_lds, cbl + 8 * KBASE(0), r32, hi, S.qr);
.LBB0_227:
	v_mov_b32_e32 v2, v0
	v_readfirstlane_b32 s85, v0
	v_ashrrev_i32_e32 v3, 4, v2
	v_and_b32_e32 v4, 0xfffff0, v3
	v_lshlrev_b32_e32 v5, 1, v3
	v_and_or_b32 v4, v5, 8, v4
	v_lshrrev_b32_e32 v5, 1, v3
	v_and_b32_e32 v7, 3, v3
	v_add_u32_e32 v3, 32, v3
	v_and_or_b32 v5, v5, 4, v7
	v_and_b32_e32 v7, 0xfffff0, v3
	v_lshlrev_b32_e32 v3, 1, v3
	v_and_or_b32 v3, v3, 8, v7
	s_lshr_b32 s69, s85, 6
	v_lshrrev_b32_e32 v4, 1, v4
	v_bfe_u32 v6, v2, 2, 2
	v_lshrrev_b32_e32 v3, 1, v3
	s_lshl_b32 s14, s69, 5
	v_or_b32_e32 v4, v4, v6
	v_lshlrev_b32_e32 v2, 4, v2
	v_or_b32_e32 v3, v3, v6
	s_add_i32 s89, s84, 0x100
	s_add_i32 s76, s14, s84
	v_lshlrev_b32_e32 v4, 9, v4
	v_and_b32_e32 v2, 48, v2
	v_lshlrev_b32_e32 v3, 9, v3
	v_lshl_add_u32 v5, v5, 6, 0
	s_lshr_b32 s77, s89, 6
	v_add_u32_e32 v213, s76, v198
	v_add3_u32 v4, v5, v4, v2
	v_add3_u32 v2, v5, v3, v2
	ds_write_b128 v4, v[102:105]
	ds_write_b128 v2, v[98:101]
	s_andn2_b32 s89, s89, 63
	s_addk_i32 s89, 0xff80
	v_or_b32_e32 v2, s89, v192
	v_mov_b32_e32 v3, v183
	v_or_b32_e32 v6, 32, v192
	v_lshlrev_b64 v[2:3], 11, v[2:3]
	v_or_b32_e32 v6, s89, v6
	v_mov_b32_e32 v7, v183
	v_lshl_add_u64 v[4:5], s[74:75], 0, v[2:3]
	v_lshlrev_b64 v[6:7], 11, v[6:7]
	v_lshl_add_u64 v[4:5], v[4:5], 0, v[182:183]
	v_lshl_add_u64 v[8:9], s[74:75], 0, v[6:7]
	v_lshl_add_u64 v[2:3], s[4:5], 0, v[2:3]
	v_lshl_add_u64 v[8:9], v[8:9], 0, v[182:183]
	global_load_dwordx4 v[46:49], v[4:5], off
	global_load_dwordx4 v[42:45], v[8:9], off
	v_lshl_add_u64 v[2:3], v[2:3], 0, v[182:183]
	v_lshl_add_u64 v[4:5], s[4:5], 0, v[6:7]
	v_lshl_add_u64 v[4:5], v[4:5], 0, v[182:183]
	global_load_dwordx4 v[34:37], v[2:3], off
	global_load_dwordx4 v[38:41], v[4:5], off
	s_add_i32 s89, s77, -1
	v_lshl_add_u32 v58, s89, 8, v200
	ds_read_b128 v[18:21], v58 offset:0
	ds_read_b128 v[22:25], v58 offset:32
	ds_read_b128 v[26:29], v58 offset:64
	ds_read_b128 v[30:33], v58 offset:96
	ds_read_b128 v[2:5], v58 offset:128
	ds_read_b128 v[6:9], v58 offset:160
	ds_read_b128 v[10:13], v58 offset:192
	ds_read_b128 v[14:17], v58 offset:224
	ds_read_b128 v[50:53], v205 offset:32768
	ds_read_b128 v[54:57], v205 offset:32896
	s_lshl_b32 s89, s89, 6
	s_or_b32 s90, s89, 63
	s_cmp_le_i32 s90, s76
	s_waitcnt lgkmcnt(1)
	v_mfma_f32_32x32x16_bf16 v[18:33], v[50:53], v[158:161], v[18:33]
	ds_read_b128 v[50:53], v205 offset:40960
	ds_read_b128 v[58:61], v205 offset:41088
	s_waitcnt lgkmcnt(1)
	v_mfma_f32_32x32x16_bf16 v[2:17], v[50:53], v[158:161], v[2:17]
	ds_read_b128 v[50:53], v206 offset:32768
	ds_read_b128 v[62:65], v206 offset:32896
	s_waitcnt lgkmcnt(1)
	v_mfma_f32_32x32x16_bf16 v[18:33], v[50:53], v[154:157], v[18:33]
	ds_read_b128 v[50:53], v206 offset:40960
	ds_read_b128 v[66:69], v206 offset:41088
	s_waitcnt lgkmcnt(1)
	v_mfma_f32_32x32x16_bf16 v[2:17], v[50:53], v[154:157], v[2:17]
	ds_read_b128 v[50:53], v207 offset:32768
	ds_read_b128 v[70:73], v207 offset:32896
	s_waitcnt lgkmcnt(1)
	v_mfma_f32_32x32x16_bf16 v[18:33], v[50:53], v[150:153], v[18:33]
	ds_read_b128 v[50:53], v207 offset:40960
	ds_read_b128 v[74:77], v207 offset:41088
	s_waitcnt lgkmcnt(1)
	v_mfma_f32_32x32x16_bf16 v[2:17], v[50:53], v[150:153], v[2:17]
	ds_read_b128 v[50:53], v208 offset:32768
	ds_read_b128 v[78:81], v208 offset:32896
	s_waitcnt lgkmcnt(1)
	v_mfma_f32_32x32x16_bf16 v[18:33], v[50:53], v[146:149], v[18:33]
	ds_read_b128 v[50:53], v208 offset:40960
	ds_read_b128 v[82:85], v208 offset:41088
	s_waitcnt lgkmcnt(1)
	v_mfma_f32_32x32x16_bf16 v[2:17], v[50:53], v[146:149], v[2:17]
	v_mfma_f32_32x32x16_bf16 v[18:33], v[54:57], v[142:145], v[18:33]
	v_mfma_f32_32x32x16_bf16 v[2:17], v[58:61], v[142:145], v[2:17]
	v_mfma_f32_32x32x16_bf16 v[18:33], v[62:65], v[138:141], v[18:33]
	v_mfma_f32_32x32x16_bf16 v[2:17], v[66:69], v[138:141], v[2:17]
	v_mfma_f32_32x32x16_bf16 v[18:33], v[70:73], v[134:137], v[18:33]
	v_mfma_f32_32x32x16_bf16 v[2:17], v[74:77], v[134:137], v[2:17]
	v_mfma_f32_32x32x16_bf16 v[18:33], v[78:81], v[130:133], v[18:33]
	s_waitcnt lgkmcnt(0)
	v_mfma_f32_32x32x16_bf16 v[2:17], v[82:85], v[130:133], v[2:17]
	s_cbranch_scc1 .LBB0_229
	v_subrev_u32_e32 v50, s89, v213
	v_cmp_gt_u32_e32 vcc, 2.0, v50
	v_add_u32_e32 v51, 0xbfffffe0, v50
	s_nop 5
	v_cndmask_b32_e32 v18, v209, v18, vcc
	v_cmp_lt_u32_e32 vcc, s17, v51
	v_add_u32_e32 v51, 0xbfffffff, v50
	s_nop 0
	v_cndmask_b32_e32 v2, v209, v2, vcc
	v_cmp_lt_u32_e32 vcc, s17, v51
	v_add_u32_e32 v51, 0xbfffffdf, v50
	s_nop 0
	v_cndmask_b32_e32 v19, v209, v19, vcc
	v_cmp_lt_u32_e32 vcc, s17, v51
	v_add_u32_e32 v51, 0xbffffffe, v50
	s_nop 0
	v_cndmask_b32_e32 v3, v209, v3, vcc
	v_cmp_lt_u32_e32 vcc, s17, v51
	v_add_u32_e32 v51, 0xbfffffde, v50
	s_nop 0
	v_cndmask_b32_e32 v20, v209, v20, vcc
	v_cmp_lt_u32_e32 vcc, s17, v51
	v_add_u32_e32 v51, 0xbffffffd, v50
	s_nop 0
	v_cndmask_b32_e32 v4, v209, v4, vcc
	v_cmp_lt_u32_e32 vcc, s17, v51
	v_add_u32_e32 v51, 0xbfffffdd, v50
	s_nop 0
	v_cndmask_b32_e32 v21, v209, v21, vcc
	v_cmp_lt_u32_e32 vcc, s17, v51
	v_add_u32_e32 v51, 0xbffffff8, v50
	s_nop 0
	v_cndmask_b32_e32 v5, v209, v5, vcc
	v_cmp_lt_u32_e32 vcc, s17, v51
	v_add_u32_e32 v51, 0xbfffffd8, v50
	s_nop 0
	v_cndmask_b32_e32 v22, v209, v22, vcc
	v_cmp_lt_u32_e32 vcc, s17, v51
	v_add_u32_e32 v51, 0xbffffff7, v50
	s_nop 0
	v_cndmask_b32_e32 v6, v209, v6, vcc
	v_cmp_lt_u32_e32 vcc, s17, v51
	v_add_u32_e32 v51, 0xbfffffd7, v50
	s_nop 0
	v_cndmask_b32_e32 v23, v209, v23, vcc
	v_cmp_lt_u32_e32 vcc, s17, v51
	v_add_u32_e32 v51, 0xbffffff6, v50
	s_nop 0
	v_cndmask_b32_e32 v7, v209, v7, vcc
	v_cmp_lt_u32_e32 vcc, s17, v51
	v_add_u32_e32 v51, 0xbfffffd6, v50
	s_nop 0
	v_cndmask_b32_e32 v24, v209, v24, vcc
	v_cmp_lt_u32_e32 vcc, s17, v51
; __device__ __forceinline__ void mask_tile(f32x16& p0, f32x16& p1, int dq, unsigned W) {
;     const float NEG = -__builtin_inff();
; #pragma unroll
;     for (int r = 0; r < 16; ++r) {
;         const int c = (r & 3) + 8 * (r >> 2);
;         if ((unsigned)(dq - c) >= W) p0[r] = NEG;
;         if ((unsigned)(dq - c - 32) >= W) p1[r] = NEG;
;     }
; }
; __device__ __forceinline__ void partialSM(f32x16& p0, f32x16& p1, float& m_reg, float& mn, float& alpha) {
;     float pmax = p0[0]; for (int r = 1; r < 16; ++r) pmax = fmaxf(pmax, p0[r]); for (int r = 0; r < 16; ++r) pmax = fmaxf(pmax, p1[r]);
;     { auto rr = __builtin_amdgcn_permlane32_swap(__float_as_uint(pmax), __float_as_uint(pmax), false, false);
;       pmax = fmaxf(__uint_as_float(rr[0]), __uint_as_float(rr[1])); }
;     constexpr float C2 = 1.4426950408889634f * SCALE;
;     if (__builtin_expect(__all((pmax - m_reg) * SCALE <= THR), 1)) { mn = m_reg; alpha = 1.f; }
;     else { mn = fmaxf(m_reg, pmax); alpha = __builtin_amdgcn_exp2f((m_reg - mn) * C2); m_reg = mn; }
;     const float mnL = -mn * C2;
;     for (int r = 0; r < 16; ++r) p0[r] = fmaf(p0[r], C2, mnL); for (int r = 0; r < 16; ++r) p1[r] = fmaf(p1[r], C2, mnL);
;     for (int r = 0; r < 16; ++r) p0[r] = __builtin_amdgcn_exp2f(p0[r]);
; }
	v_add_u32_e32 v51, 0xbffffff5, v50
	s_nop 0
	v_cndmask_b32_e32 v8, v209, v8, vcc
	v_cmp_lt_u32_e32 vcc, s17, v51
	v_add_u32_e32 v51, 0xbfffffd5, v50
	s_nop 0
	v_cndmask_b32_e32 v25, v209, v25, vcc
	v_cmp_lt_u32_e32 vcc, s17, v51
	v_add_u32_e32 v51, 0xbffffff0, v50
	s_nop 0
	v_cndmask_b32_e32 v9, v209, v9, vcc
	v_cmp_lt_u32_e32 vcc, s17, v51
	v_add_u32_e32 v51, 0xbfffffd0, v50
	s_nop 0
	v_cndmask_b32_e32 v26, v209, v26, vcc
	v_cmp_lt_u32_e32 vcc, s17, v51
	v_add_u32_e32 v51, 0xbfffffef, v50
	s_nop 0
	v_cndmask_b32_e32 v10, v209, v10, vcc
	v_cmp_lt_u32_e32 vcc, s17, v51
	v_add_u32_e32 v51, 0xbfffffcf, v50
	s_nop 0
	v_cndmask_b32_e32 v27, v209, v27, vcc
	v_cmp_lt_u32_e32 vcc, s17, v51
	v_add_u32_e32 v51, 0xbfffffee, v50
	s_nop 0
	v_cndmask_b32_e32 v11, v209, v11, vcc
	v_cmp_lt_u32_e32 vcc, s17, v51
	v_add_u32_e32 v51, 0xbfffffce, v50
	s_nop 0
	v_cndmask_b32_e32 v28, v209, v28, vcc
	v_cmp_lt_u32_e32 vcc, s17, v51
	v_add_u32_e32 v51, 0xbfffffed, v50
	s_nop 0
	v_cndmask_b32_e32 v12, v209, v12, vcc
	v_cmp_lt_u32_e32 vcc, s17, v51
	v_add_u32_e32 v51, 0xbfffffcd, v50
	s_nop 0
	v_cndmask_b32_e32 v29, v209, v29, vcc
	v_cmp_lt_u32_e32 vcc, s17, v51
	v_add_u32_e32 v51, 0xbfffffe8, v50
	s_nop 0
	v_cndmask_b32_e32 v13, v209, v13, vcc
	v_cmp_lt_u32_e32 vcc, s17, v51
	v_add_u32_e32 v51, 0xbfffffc8, v50
	s_nop 0
	v_cndmask_b32_e32 v30, v209, v30, vcc
	v_cmp_lt_u32_e32 vcc, s17, v51
	v_add_u32_e32 v51, 0xbfffffe7, v50
	s_nop 0
	v_cndmask_b32_e32 v14, v209, v14, vcc
	v_cmp_lt_u32_e32 vcc, s17, v51
	v_add_u32_e32 v51, 0xbfffffc7, v50
	s_nop 0
	v_cndmask_b32_e32 v31, v209, v31, vcc
	v_cmp_lt_u32_e32 vcc, s17, v51
	v_add_u32_e32 v51, 0xbfffffe6, v50
	s_nop 0
	v_cndmask_b32_e32 v15, v209, v15, vcc
	v_cmp_lt_u32_e32 vcc, s17, v51
	v_add_u32_e32 v51, 0xbfffffc6, v50
	s_nop 0
	v_cndmask_b32_e32 v32, v209, v32, vcc
	v_cmp_lt_u32_e32 vcc, s17, v51
	v_add_u32_e32 v51, 0xbfffffe5, v50
	v_add_u32_e32 v50, 0xbfffffc5, v50
	v_cndmask_b32_e32 v16, v209, v16, vcc
	v_cmp_lt_u32_e32 vcc, s17, v51
	s_nop 1
	v_cndmask_b32_e32 v33, v209, v33, vcc
	v_cmp_lt_u32_e32 vcc, s17, v50
	s_nop 1
	v_cndmask_b32_e32 v17, v209, v17, vcc
.LBB0_229:
	s_nop 8
	v_max_f32_e32 v50, v19, v19
	v_max_f32_e32 v51, v18, v18
	v_max_f32_e32 v50, v51, v50
	v_max3_f32 v50, v50, v20, v21
	v_max3_f32 v50, v50, v22, v23
	v_max3_f32 v50, v50, v24, v25
	v_max3_f32 v50, v50, v26, v27
	v_max3_f32 v50, v50, v28, v29
	v_max3_f32 v50, v50, v30, v31
	v_max3_f32 v50, v50, v32, v33
	v_max3_f32 v50, v50, v2, v3
	v_max3_f32 v50, v50, v4, v5
	v_max3_f32 v50, v50, v6, v7
	v_max3_f32 v50, v50, v8, v9
	v_max3_f32 v50, v50, v10, v11
	v_max3_f32 v50, v50, v12, v13
	v_max3_f32 v50, v50, v14, v15
	v_max3_f32 v50, v50, v16, v17
	v_mov_b32_e32 v51, v50
	s_nop 1
	v_permlane32_swap_b32_e32 v50, v51
	v_max_f32_e32 v51, v51, v51
	v_max_f32_e32 v50, v50, v50
	v_max_f32_e32 v50, v50, v51
	s_and_b32 s89, s85, 0x3fffffc0
	v_add_f32_e32 v51, 0x7149f2ca, v50
	s_lshl_b32 s89, s89, 2
	v_mul_f32_e32 v51, 0x3db504f3, v51
	v_max_f32_e32 v50, 0xf149f2ca, v50
	s_add_i32 s89, s89, 0
	v_cmp_ge_f32_e32 vcc, s78, v51
	v_sub_f32_e32 v51, 0xf149f2ca, v50
	s_add_i32 s89, s89, 0x10000
	v_mul_f32_e32 v51, 0x3e0293ee, v51
	v_exp_f32_e32 v51, v51
	s_cmp_eq_u64 vcc, exec
	s_cselect_b64 vcc, -1, 0
	v_cndmask_b32_e32 v217, v50, v210, vcc
	v_mul_f32_e32 v50, 0xbe0293ee, v217
	v_cndmask_b32_e64 v187, v51, 1.0, vcc
	v_mov_b32_e32 v51, v50
	v_fmac_f32_e32 v51, 0x3e0293ee, v33
	v_pk_fma_f32 v[126:127], v[2:3], s[16:17], v[50:51] op_sel_hi:[1,0,0]
	v_mov_b32_e32 v2, v0
	s_waitcnt vmcnt(0)
	v_pk_fma_f32 v[124:125], v[4:5], s[16:17], v[50:51] op_sel_hi:[1,0,0]
	v_ashrrev_i32_e32 v3, 4, v2
	v_and_b32_e32 v4, 0xfffff0, v3
	v_lshlrev_b32_e32 v5, 1, v3
	v_pk_fma_f32 v[120:121], v[6:7], s[16:17], v[50:51] op_sel_hi:[1,0,0]
	v_and_or_b32 v4, v5, 8, v4
	v_lshrrev_b32_e32 v5, 1, v3
	v_and_b32_e32 v7, 3, v3
	v_add_u32_e32 v3, 32, v3
	v_and_or_b32 v5, v5, 4, v7
	v_and_b32_e32 v7, 0xfffff0, v3
	v_lshlrev_b32_e32 v3, 1, v3
	v_and_or_b32 v3, v3, 8, v7
	v_lshrrev_b32_e32 v4, 1, v4
	v_bfe_u32 v6, v2, 2, 2
	v_lshrrev_b32_e32 v3, 1, v3
	v_or_b32_e32 v4, v4, v6
	v_lshlrev_b32_e32 v2, 4, v2
	v_or_b32_e32 v3, v3, v6
	v_lshlrev_b32_e32 v4, 9, v4
	v_and_b32_e32 v2, 48, v2
	v_lshlrev_b32_e32 v3, 9, v3
	v_lshl_add_u32 v5, v5, 6, 0
	v_add3_u32 v4, v5, v4, v2
	v_add3_u32 v2, v5, v3, v2
	s_waitcnt vmcnt(3)
	ds_write_b128 v4, v[46:49] offset:16384
	s_waitcnt vmcnt(2)
	ds_write_b128 v2, v[42:45] offset:16384
	v_mov_b32_e32 v2, v0
	v_fmamk_f32 v18, v18, 0x3e0293ee, v50
	v_lshlrev_b32_e32 v3, 4, v2
	v_and_b32_e32 v2, 0x70, v2
	v_and_b32_e32 v4, 0xffffff00, v3
	v_bitop3_b32 v2, v3, v2, s79 bitop3:0x6c
	v_fmamk_f32 v19, v19, 0x3e0293ee, v50
	v_fmamk_f32 v20, v20, 0x3e0293ee, v50
	v_fmamk_f32 v21, v21, 0x3e0293ee, v50
	v_fmamk_f32 v22, v22, 0x3e0293ee, v50
	v_fmamk_f32 v23, v23, 0x3e0293ee, v50
	v_fmamk_f32 v24, v24, 0x3e0293ee, v50
	v_fmamk_f32 v25, v25, 0x3e0293ee, v50
	v_fmamk_f32 v26, v26, 0x3e0293ee, v50
	v_fmamk_f32 v27, v27, 0x3e0293ee, v50
	v_fmamk_f32 v28, v28, 0x3e0293ee, v50
	v_fmamk_f32 v29, v29, 0x3e0293ee, v50
	v_fmamk_f32 v30, v30, 0x3e0293ee, v50
	v_fmamk_f32 v31, v31, 0x3e0293ee, v50
	v_fmamk_f32 v32, v32, 0x3e0293ee, v50
	v_add3_u32 v2, 0, v4, v2
	v_exp_f32_e32 v234, v18
	v_exp_f32_e32 v236, v19
	v_exp_f32_e32 v232, v20
	v_exp_f32_e32 v235, v21
	v_exp_f32_e32 v231, v22
	v_exp_f32_e32 v233, v23
	v_exp_f32_e32 v229, v24
	v_exp_f32_e32 v230, v25
	v_exp_f32_e32 v226, v26
	v_exp_f32_e32 v228, v27
	v_exp_f32_e32 v225, v28
	v_exp_f32_e32 v227, v29
	v_exp_f32_e32 v222, v30
	v_exp_f32_e32 v224, v31
	v_exp_f32_e32 v221, v32
	v_exp_f32_e32 v223, v51
	s_waitcnt vmcnt(1)
; __device__ __forceinline__ void finishSM(f32x16& p0, f32x16& p1, float alpha, float& l_reg, bf16x8& pa0, bf16x8& pa1, bf16x8& pa2, bf16x8& pa3) {
;     for (int r = 0; r < 16; ++r) p1[r] = __builtin_amdgcn_exp2f(p1[r]);
;     float ps = 0; for (int r = 0; r < 16; ++r) ps += p0[r]; for (int r = 0; r < 16; ++r) ps += p1[r];
; template <int KB>
; __device__ __forceinline__ void qkt(f32x16& p0, f32x16& p1, const char* K_lds, const char* cbt, int r32, int hi, const bf16x8* qr) {
;     { const u32x2 e0 = *(const u32x2*)(cbt), e1 = *(const u32x2*)(cbt + 32 * 8);
;       const unsigned c0 = hi ? 0u : 0x3F803F80u, c1 = hi ? 0u : 0x00003F80u;
;       const u32x4 k0 = {e0.x, e0.y, e0.x, e0.y}, k1 = {e1.x, e1.y, e1.x, e1.y}, q1 = {c0, c1, 0u, 0u};
;       p0 = __builtin_amdgcn_mfma_f32_32x32x16_bf16(__builtin_bit_cast(bf16x8, k0), __builtin_bit_cast(bf16x8, q1), f32x16{}, 0, 0, 0);
;       p1 = __builtin_amdgcn_mfma_f32_32x32x16_bf16(__builtin_bit_cast(bf16x8, k1), __builtin_bit_cast(bf16x8, q1), f32x16{}, 0, 0, 0); }
;     const char* kb[4];
; #pragma unroll
;     for (int dd = 0; dd < 4; ++dd) kb[dd] = K_lds + KB * SHM_K + KSWZ(r32, (dd * 16 + hi * 8) * 2);
; #pragma unroll
;     for (int d0 = 0; d0 < 8; ++d0) { const char* a = kb[d0 & 3] + (d0 >> 2) * 128;
;         bf16x8 b0 = *reinterpret_cast<const bf16x8*>(a);
;         bf16x8 b1 = *reinterpret_cast<const bf16x8*>(a + 32 * 256);
;         p0 = __builtin_amdgcn_mfma_f32_32x32x16_bf16(b0, qr[d0], p0, 0, 0, 0);
;         p1 = __builtin_amdgcn_mfma_f32_32x32x16_bf16(b1, qr[d0], p1, 0, 0, 0); }
; }
	ds_write_b128 v2, v[34:37] offset:49152
	s_waitcnt vmcnt(0)
	ds_write_b128 v2, v[38:41] offset:57344
	v_add_u32_e32 v2, 0xc0, v198
	v_pk_fma_f32 v[118:119], v[16:17], s[16:17], v[50:51] op_sel_hi:[1,0,0]
	v_lshl_add_u64 v[190:191], s[4:5], 0, v[182:183]
	v_add_u32_e32 v2, s76, v2
	s_lshl_b32 s4, s77, 6
	v_mov_b32_e32 v16, v183
	v_mov_b32_e32 v17, v183
	v_pk_fma_f32 v[122:123], v[14:15], s[16:17], v[50:51] op_sel_hi:[1,0,0]
	v_pk_fma_f32 v[128:129], v[12:13], s[16:17], v[50:51] op_sel_hi:[1,0,0]
	v_pk_fma_f32 v[114:115], v[10:11], s[16:17], v[50:51] op_sel_hi:[1,0,0]
	v_pk_fma_f32 v[116:117], v[8:9], s[16:17], v[50:51] op_sel_hi:[1,0,0]
	v_subrev_u32_e32 v216, s4, v2
	v_mov_b32_e32 v2, v183
	v_mov_b32_e32 v3, v183
	v_mov_b32_e32 v4, v183
	v_mov_b32_e32 v5, v183
	v_mov_b32_e32 v6, v183
	v_mov_b32_e32 v7, v183
	v_mov_b32_e32 v8, v183
	v_mov_b32_e32 v9, v183
	v_mov_b32_e32 v10, v183
	v_mov_b32_e32 v11, v183
	v_mov_b32_e32 v12, v183
	v_mov_b32_e32 v13, v183
	v_mov_b32_e32 v14, v183
	v_mov_b32_e32 v15, v183
	v_mov_b64_e32 v[64:65], v[16:17]
	v_mov_b64_e32 v[48:49], v[16:17]
	v_mov_b64_e32 v[32:33], v[16:17]
	s_mov_b32 s85, 2
	v_lshl_add_u64 v[188:189], s[74:75], 0, v[182:183]
	v_lshl_add_u32 v212, v1, 2, s89
	v_lshl_add_u32 v211, v203, 2, s89
	v_lshl_add_u32 v215, s77, 8, v202
	s_add_i32 s89, s4, 0xffffffbf
	v_mov_b32_e32 v214, 0
	v_mov_b64_e32 v[62:63], v[14:15]
	v_mov_b64_e32 v[60:61], v[12:13]
	v_mov_b64_e32 v[58:59], v[10:11]
	v_mov_b64_e32 v[56:57], v[8:9]
	v_mov_b64_e32 v[54:55], v[6:7]
	v_mov_b64_e32 v[52:53], v[4:5]
	v_mov_b64_e32 v[50:51], v[2:3]
	v_mov_b64_e32 v[46:47], v[14:15]
	v_mov_b64_e32 v[44:45], v[12:13]
	v_mov_b64_e32 v[42:43], v[10:11]
	v_mov_b64_e32 v[40:41], v[8:9]
	v_mov_b64_e32 v[38:39], v[6:7]
	v_mov_b64_e32 v[36:37], v[4:5]
	v_mov_b64_e32 v[34:35], v[2:3]
	v_mov_b64_e32 v[30:31], v[14:15]
	v_mov_b64_e32 v[28:29], v[12:13]
	v_mov_b64_e32 v[26:27], v[10:11]
	v_mov_b64_e32 v[24:25], v[8:9]
	v_mov_b64_e32 v[22:23], v[6:7]
	v_mov_b64_e32 v[20:21], v[4:5]
	v_mov_b64_e32 v[18:19], v[2:3]
	v_and_b32_e32 v239, 0x70, v0
	v_and_b32_e32 v201, 0xffffff00, v184
	v_and_b32_e32 v1, 0xf0, v184
	v_xor_b32_e32 v1, v1, v239
	v_add_u32_e32 v201, v201, v1
	v_bfe_u32 v1, v0, 6, 1
	v_lshlrev_b32_e32 v1, 11, v1
	v_bfe_u32 v239, v0, 8, 1
	v_lshl_or_b32 v1, v239, 12, v1
	v_bfe_u32 v239, v0, 2, 2
	v_lshl_or_b32 v1, v239, 9, v1
	v_bfe_u32 v239, v0, 4, 2
	v_lshl_or_b32 v1, v239, 6, v1
	v_bfe_u32 v239, v0, 7, 1
	v_lshl_or_b32 v1, v239, 8, v1
	v_and_b32_e32 v239, 3, v0
	v_lshl_or_b32 v1, v239, 4, v1
	v_lshlrev_b32_e32 v239, 2, v0
	s_waitcnt lgkmcnt(0)
	s_barrier
.LBB0_230:
	v_add_u32_e32 v102, s89, v192
	v_add_u32_e32 v66, 0xffffff81, v102
	v_ashrrev_i32_e32 v67, 31, v66
	v_add_u32_e32 v70, 0xffffffa1, v102
	v_lshlrev_b64 v[66:67], 11, v[66:67]
	v_ashrrev_i32_e32 v71, 31, v70
	v_lshl_add_u64 v[68:69], v[188:189], 0, v[66:67]
	v_lshlrev_b64 v[70:71], 11, v[70:71]
	v_lshl_add_u64 v[66:67], v[190:191], 0, v[66:67]
	v_lshl_add_u64 v[72:73], v[188:189], 0, v[70:71]
	global_load_dwordx4 v[174:177], v[68:69], off
	global_load_dwordx4 v[170:173], v[72:73], off
	v_lshl_add_u64 v[68:69], v[190:191], 0, v[70:71]
	global_load_dwordx4 v[166:169], v[66:67], off
	global_load_dwordx4 v[178:181], v[68:69], off
	ds_read_b128 v[86:89], v215 offset:256
	ds_read_b128 v[90:93], v215 offset:288
	ds_read_b128 v[94:97], v215 offset:320
	ds_read_b128 v[98:101], v215 offset:352
	ds_read_b128 v[70:73], v215 offset:384
	ds_read_b128 v[74:77], v215 offset:416
	ds_read_b128 v[78:81], v215 offset:448
	ds_read_b128 v[82:85], v215 offset:480
	v_exp_f32_e32 v103, v126
	v_exp_f32_e32 v108, v127
	v_exp_f32_e32 v109, v124
	v_exp_f32_e32 v110, v125
	v_exp_f32_e32 v111, v120
	v_exp_f32_e32 v112, v121
	v_exp_f32_e32 v113, v116
	v_exp_f32_e32 v116, v117
	v_exp_f32_e32 v114, v114
	v_exp_f32_e32 v115, v115
	v_exp_f32_e32 v117, v128
	ds_read_b128 v[162:165], v205 offset:49152
	ds_read_b128 v[182:185], v205 offset:57344
	v_exp_f32_e32 v120, v129
	v_exp_f32_e32 v121, v122
	v_exp_f32_e32 v122, v123
	v_exp_f32_e32 v118, v118
	v_exp_f32_e32 v119, v119
	s_waitcnt lgkmcnt(1)
	v_mfma_f32_32x32x16_bf16 v[86:101], v[162:165], v[158:161], v[86:101]
	v_add_f32_e32 v66, 0, v234
	v_add_f32_e32 v66, v236, v66
	v_add_f32_e32 v66, v232, v66
	v_add_f32_e32 v66, v235, v66
	s_waitcnt lgkmcnt(0)
	v_mfma_f32_32x32x16_bf16 v[70:85], v[182:185], v[158:161], v[70:85]
	ds_read_b128 v[162:165], v206 offset:49152
	ds_read_b128 v[182:185], v206 offset:57344
	v_add_f32_e32 v66, v231, v66
	v_add_f32_e32 v66, v233, v66
	v_add_f32_e32 v66, v229, v66
	v_add_f32_e32 v66, v230, v66
	s_waitcnt lgkmcnt(1)
	v_mfma_f32_32x32x16_bf16 v[86:101], v[162:165], v[154:157], v[86:101]
	v_add_f32_e32 v66, v226, v66
	v_add_f32_e32 v66, v228, v66
	v_add_f32_e32 v66, v225, v66
	v_add_f32_e32 v66, v227, v66
	s_waitcnt lgkmcnt(0)
	v_mfma_f32_32x32x16_bf16 v[70:85], v[182:185], v[154:157], v[70:85]
	ds_read_b128 v[162:165], v207 offset:49152
	ds_read_b128 v[182:185], v207 offset:57344
	v_add_f32_e32 v66, v222, v66
	v_add_f32_e32 v66, v224, v66
	v_add_f32_e32 v66, v221, v66
	v_add_f32_e32 v66, v223, v66
	s_waitcnt lgkmcnt(1)
	v_mfma_f32_32x32x16_bf16 v[86:101], v[162:165], v[150:153], v[86:101]
	v_add_f32_e32 v66, v103, v66
	v_add_f32_e32 v66, v108, v66
	v_add_f32_e32 v66, v109, v66
	v_add_f32_e32 v66, v110, v66
	s_waitcnt lgkmcnt(0)
	v_mfma_f32_32x32x16_bf16 v[70:85], v[182:185], v[150:153], v[70:85]
	ds_read_b128 v[162:165], v208 offset:49152
	ds_read_b128 v[182:185], v208 offset:57344
	v_add_f32_e32 v66, v111, v66
	v_add_f32_e32 v66, v112, v66
	v_add_f32_e32 v66, v113, v66
	v_add_f32_e32 v66, v116, v66
	s_waitcnt lgkmcnt(1)
; __device__ __forceinline__ void finishSM(f32x16& p0, f32x16& p1, float alpha, float& l_reg, bf16x8& pa0, bf16x8& pa1, bf16x8& pa2, bf16x8& pa3) {
;     for (int r = 0; r < 16; ++r) p1[r] = __builtin_amdgcn_exp2f(p1[r]);
;     float ps = 0; for (int r = 0; r < 16; ++r) ps += p0[r]; for (int r = 0; r < 16; ++r) ps += p1[r];
;     { auto rr = __builtin_amdgcn_permlane32_swap(__float_as_uint(ps), __float_as_uint(ps), false, false);
;       ps = __uint_as_float(rr[0]) + __uint_as_float(rr[1]); }
;     l_reg = l_reg * alpha + ps;
;     ...
;     PK4(p0, 0, pa0); PK4(p0, 8, pa1); PK4(p1, 0, pa2); PK4(p1, 8, pa3);
; template <int VB>
; __device__ __forceinline__ void pv_tile(f32x16* o, int vb0, bf16x8 pa0, bf16x8 pa1, bf16x8 pa2, bf16x8 pa3) {
;     ...
;     PV_R(0, 0, pa0, pa1); PV_R(0, 2, pa2, pa3); PV_R(2, 0, pa0, pa1); PV_R(2, 2, pa2, pa3);
	v_mfma_f32_32x32x16_bf16 v[86:101], v[162:165], v[146:149], v[86:101]
	v_add_f32_e32 v66, v114, v66
	v_add_f32_e32 v66, v115, v66
	v_add_f32_e32 v66, v117, v66
	v_add_f32_e32 v66, v120, v66
	s_waitcnt lgkmcnt(0)
	v_mfma_f32_32x32x16_bf16 v[70:85], v[182:185], v[146:149], v[70:85]
	ds_read_b128 v[162:165], v205 offset:49280
	ds_read_b128 v[182:185], v205 offset:57472
	v_add_f32_e32 v66, v121, v66
	v_add_f32_e32 v66, v122, v66
	v_add_f32_e32 v66, v118, v66
	v_add_f32_e32 v218, v119, v66
	s_waitcnt lgkmcnt(1)
	v_mfma_f32_32x32x16_bf16 v[86:101], v[162:165], v[142:145], v[86:101]
	v_mov_b32_e32 v219, v218
	s_nop 1
	v_permlane32_swap_b32_e32 v218, v219
	s_waitcnt lgkmcnt(0)
	v_mfma_f32_32x32x16_bf16 v[70:85], v[182:185], v[142:145], v[70:85]
	ds_read_b128 v[162:165], v206 offset:49280
	ds_read_b128 v[182:185], v206 offset:57472
	v_cvt_pk_bf16_f32 v66, v234, v236
	v_cvt_pk_bf16_f32 v67, v232, v235
	v_cvt_pk_bf16_f32 v68, v231, v233
	v_cvt_pk_bf16_f32 v69, v229, v230
	s_waitcnt lgkmcnt(1)
	v_mfma_f32_32x32x16_bf16 v[86:101], v[162:165], v[138:141], v[86:101]
	v_cvt_pk_bf16_f32 v104, v226, v228
	v_cvt_pk_bf16_f32 v105, v225, v227
	v_cvt_pk_bf16_f32 v106, v222, v224
	v_cvt_pk_bf16_f32 v107, v221, v223
	s_waitcnt lgkmcnt(0)
	v_mfma_f32_32x32x16_bf16 v[70:85], v[182:185], v[138:141], v[70:85]
	ds_read_b128 v[162:165], v207 offset:49280
	ds_read_b128 v[182:185], v207 offset:57472
	v_cvt_pk_bf16_f32 v108, v103, v108
	v_cvt_pk_bf16_f32 v109, v109, v110
	v_cvt_pk_bf16_f32 v110, v111, v112
	v_cvt_pk_bf16_f32 v111, v113, v116
	s_waitcnt lgkmcnt(1)
	v_mfma_f32_32x32x16_bf16 v[86:101], v[162:165], v[134:137], v[86:101]
	v_cvt_pk_bf16_f32 v112, v114, v115
	v_cvt_pk_bf16_f32 v113, v117, v120
	v_cvt_pk_bf16_f32 v114, v121, v122
	v_cvt_pk_bf16_f32 v115, v118, v119
	s_waitcnt lgkmcnt(0)
	v_mfma_f32_32x32x16_bf16 v[70:85], v[182:185], v[134:137], v[70:85]
	ds_read_b128 v[162:165], v208 offset:49280
	ds_read_b128 v[182:185], v208 offset:57472
	v_permlane32_swap_b32_e32 v66, v68
	v_permlane32_swap_b32_e32 v67, v69
	v_permlane32_swap_b32_e32 v104, v106
	v_permlane32_swap_b32_e32 v105, v107
	s_waitcnt lgkmcnt(1)
	v_mfma_f32_32x32x16_bf16 v[86:101], v[162:165], v[130:133], v[86:101]
	v_permlane32_swap_b32_e32 v108, v110
	v_permlane32_swap_b32_e32 v109, v111
	v_permlane32_swap_b32_e32 v112, v114
	v_permlane32_swap_b32_e32 v113, v115
	s_waitcnt lgkmcnt(0)
	v_mfma_f32_32x32x16_bf16 v[70:85], v[182:185], v[130:133], v[70:85]
	ds_read_b64_tr_b16 v[116:117], v199 offset:0
	ds_read_b64_tr_b16 v[118:119], v199 offset:0x800
	ds_read_b64_tr_b16 v[120:121], v199 offset:0x200
	ds_read_b64_tr_b16 v[122:123], v199 offset:0xa00
	ds_read_b64_tr_b16 v[124:125], v199 offset:0x1000
	ds_read_b64_tr_b16 v[126:127], v199 offset:0x1800
	ds_read_b64_tr_b16 v[220:221], v199 offset:0x1200
	ds_read_b64_tr_b16 v[222:223], v199 offset:0x1a00
	s_waitcnt lgkmcnt(0)
	s_nop 0
	v_mfma_f32_32x32x16_bf16 v[2:17], v[66:69], v[116:119], v[2:17]
	ds_read_b64_tr_b16 v[116:117], v199 offset:0x2000
	ds_read_b64_tr_b16 v[118:119], v199 offset:0x2800
	v_mfma_f32_32x32x16_bf16 v[50:65], v[66:69], v[120:123], v[50:65]
	ds_read_b64_tr_b16 v[120:121], v199 offset:0x2200
	ds_read_b64_tr_b16 v[122:123], v199 offset:0x2a00
	v_mfma_f32_32x32x16_bf16 v[2:17], v[104:107], v[124:127], v[2:17]
	ds_read_b64_tr_b16 v[124:125], v199 offset:0x3000
	ds_read_b64_tr_b16 v[126:127], v199 offset:0x3800
	ds_read_b64_tr_b16 v[224:225], v199 offset:0x3200
	ds_read_b64_tr_b16 v[226:227], v199 offset:0x3a00
	s_waitcnt lgkmcnt(0)
	v_mfma_f32_32x32x16_bf16 v[50:65], v[104:107], v[220:223], v[50:65]
	v_mfma_f32_32x32x16_bf16 v[2:17], v[108:111], v[116:119], v[2:17]
	ds_read_b64_tr_b16 v[116:117], v199 offset:0x400
	ds_read_b64_tr_b16 v[118:119], v199 offset:0xc00
	v_mfma_f32_32x32x16_bf16 v[50:65], v[108:111], v[120:123], v[50:65]
	ds_read_b64_tr_b16 v[120:121], v199 offset:0x600
	ds_read_b64_tr_b16 v[122:123], v199 offset:0xe00
	v_mfma_f32_32x32x16_bf16 v[2:17], v[112:115], v[124:127], v[2:17]
	ds_read_b64_tr_b16 v[124:125], v199 offset:0x1400
	ds_read_b64_tr_b16 v[126:127], v199 offset:0x1c00
	ds_read_b64_tr_b16 v[220:221], v199 offset:0x1600
	ds_read_b64_tr_b16 v[222:223], v199 offset:0x1e00
	s_waitcnt lgkmcnt(0)
	v_mfma_f32_32x32x16_bf16 v[50:65], v[112:115], v[224:227], v[50:65]
	v_mfma_f32_32x32x16_bf16 v[34:49], v[66:69], v[116:119], v[34:49]
	v_mfma_f32_32x32x16_bf16 v[18:33], v[66:69], v[120:123], v[18:33]
	ds_read_b64_tr_b16 v[66:67], v199 offset:0x2400
	ds_read_b64_tr_b16 v[68:69], v199 offset:0x2c00
	ds_read_b64_tr_b16 v[116:117], v199 offset:0x2600
	ds_read_b64_tr_b16 v[118:119], v199 offset:0x2e00
	ds_read_b64_tr_b16 v[120:121], v199 offset:0x3400
	ds_read_b64_tr_b16 v[122:123], v199 offset:0x3c00
	v_mfma_f32_32x32x16_bf16 v[34:49], v[104:107], v[124:127], v[34:49]
	ds_read_b64_tr_b16 v[124:125], v199 offset:0x3600
	ds_read_b64_tr_b16 v[126:127], v199 offset:0x3e00
	s_waitcnt lgkmcnt(0)
	v_mfma_f32_32x32x16_bf16 v[18:33], v[104:107], v[220:223], v[18:33]
	v_mfma_f32_32x32x16_bf16 v[34:49], v[108:111], v[66:69], v[34:49]
	s_cmp_le_i32 s89, s76
	v_mfma_f32_32x32x16_bf16 v[18:33], v[108:111], v[116:119], v[18:33]
	v_mfma_f32_32x32x16_bf16 v[34:49], v[112:115], v[120:123], v[34:49]
	v_mfma_f32_32x32x16_bf16 v[18:33], v[112:115], v[124:127], v[18:33]
	s_cbranch_scc1 .LBB0_232
; __device__ __forceinline__ void mask_tile(f32x16& p0, f32x16& p1, int dq, unsigned W) {
;     const float NEG = -__builtin_inff();
; #pragma unroll
;     for (int r = 0; r < 16; ++r) {
;         const int c = (r & 3) + 8 * (r >> 2);
;         if ((unsigned)(dq - c) >= W) p0[r] = NEG;
;         if ((unsigned)(dq - c - 32) >= W) p1[r] = NEG;
;     }
; }
	v_subrev_u32_e32 v66, 64, v216
	v_cmp_gt_u32_e32 vcc, 2.0, v66
	v_add_u32_e32 v66, 0xbfffffa0, v216
	s_nop 0
	v_cndmask_b32_e32 v86, v209, v86, vcc
	v_cmp_lt_u32_e32 vcc, s17, v66
	v_add_u32_e32 v66, 0xbfffffbf, v216
	s_nop 0
	v_cndmask_b32_e32 v70, v209, v70, vcc
	v_cmp_lt_u32_e32 vcc, s17, v66
	v_add_u32_e32 v66, 0xbfffff9f, v216
	s_nop 0
	v_cndmask_b32_e32 v87, v209, v87, vcc
	v_cmp_lt_u32_e32 vcc, s17, v66
	v_add_u32_e32 v66, 0xbfffffbe, v216
	s_nop 0
	v_cndmask_b32_e32 v71, v209, v71, vcc
	v_cmp_lt_u32_e32 vcc, s17, v66
	v_add_u32_e32 v66, 0xbfffff9e, v216
	s_nop 0
	v_cndmask_b32_e32 v88, v209, v88, vcc
	v_cmp_lt_u32_e32 vcc, s17, v66
	v_add_u32_e32 v66, 0xbfffffbd, v216
	s_nop 0
	v_cndmask_b32_e32 v72, v209, v72, vcc
	v_cmp_lt_u32_e32 vcc, s17, v66
	v_add_u32_e32 v66, 0xbfffff9d, v216
	s_nop 0
	v_cndmask_b32_e32 v89, v209, v89, vcc
	v_cmp_lt_u32_e32 vcc, s17, v66
	v_add_u32_e32 v66, 0xbfffffb8, v216
	s_nop 0
	v_cndmask_b32_e32 v73, v209, v73, vcc
	v_cmp_lt_u32_e32 vcc, s17, v66
	v_add_u32_e32 v66, 0xbfffff98, v216
	s_nop 0
	v_cndmask_b32_e32 v90, v209, v90, vcc
	v_cmp_lt_u32_e32 vcc, s17, v66
	v_add_u32_e32 v66, 0xbfffffb7, v216
	s_nop 0
	v_cndmask_b32_e32 v74, v209, v74, vcc
	v_cmp_lt_u32_e32 vcc, s17, v66
	v_add_u32_e32 v66, 0xbfffff97, v216
	s_nop 0
	v_cndmask_b32_e32 v91, v209, v91, vcc
	v_cmp_lt_u32_e32 vcc, s17, v66
	v_add_u32_e32 v66, 0xbfffffb6, v216
	s_nop 0
	v_cndmask_b32_e32 v75, v209, v75, vcc
	v_cmp_lt_u32_e32 vcc, s17, v66
	v_add_u32_e32 v66, 0xbfffff96, v216
	s_nop 0
	v_cndmask_b32_e32 v92, v209, v92, vcc
	v_cmp_lt_u32_e32 vcc, s17, v66
	v_add_u32_e32 v66, 0xbfffffb5, v216
	s_nop 0
	v_cndmask_b32_e32 v76, v209, v76, vcc
	v_cmp_lt_u32_e32 vcc, s17, v66
	v_add_u32_e32 v66, 0xbfffff95, v216
	s_nop 0
	v_cndmask_b32_e32 v93, v209, v93, vcc
	v_cmp_lt_u32_e32 vcc, s17, v66
	v_add_u32_e32 v66, 0xbfffffb0, v216
	s_nop 0
	v_cndmask_b32_e32 v77, v209, v77, vcc
	v_cmp_lt_u32_e32 vcc, s17, v66
	v_add_u32_e32 v66, 0xbfffff90, v216
	s_nop 0
	v_cndmask_b32_e32 v94, v209, v94, vcc
	v_cmp_lt_u32_e32 vcc, s17, v66
	v_add_u32_e32 v66, 0xbfffffaf, v216
	s_nop 0
	v_cndmask_b32_e32 v78, v209, v78, vcc
	v_cmp_lt_u32_e32 vcc, s17, v66
	v_add_u32_e32 v66, 0xbfffff8f, v216
	s_nop 0
	v_cndmask_b32_e32 v95, v209, v95, vcc
	v_cmp_lt_u32_e32 vcc, s17, v66
	v_add_u32_e32 v66, 0xbfffffae, v216
	s_nop 0
	v_cndmask_b32_e32 v79, v209, v79, vcc
	v_cmp_lt_u32_e32 vcc, s17, v66
	v_add_u32_e32 v66, 0xbfffff8e, v216
	s_nop 0
	v_cndmask_b32_e32 v96, v209, v96, vcc
	v_cmp_lt_u32_e32 vcc, s17, v66
	v_add_u32_e32 v66, 0xbfffffad, v216
	s_nop 0
	v_cndmask_b32_e32 v80, v209, v80, vcc
	v_cmp_lt_u32_e32 vcc, s17, v66
	v_add_u32_e32 v66, 0xbfffff8d, v216
	s_nop 0
	v_cndmask_b32_e32 v97, v209, v97, vcc
	v_cmp_lt_u32_e32 vcc, s17, v66
	v_add_u32_e32 v66, 0xbfffffa8, v216
	s_nop 0
	v_cndmask_b32_e32 v81, v209, v81, vcc
	v_cmp_lt_u32_e32 vcc, s17, v66
	v_add_u32_e32 v66, 0xbfffff88, v216
	s_nop 0
	v_cndmask_b32_e32 v98, v209, v98, vcc
	v_cmp_lt_u32_e32 vcc, s17, v66
	v_add_u32_e32 v66, 0xbfffffa7, v216
	s_nop 0
	v_cndmask_b32_e32 v82, v209, v82, vcc
	v_cmp_lt_u32_e32 vcc, s17, v66
	v_add_u32_e32 v66, 0xbfffff87, v216
	s_nop 0
	v_cndmask_b32_e32 v99, v209, v99, vcc
	v_cmp_lt_u32_e32 vcc, s17, v66
	v_add_u32_e32 v66, 0xbfffffa6, v216
	s_nop 0
	v_cndmask_b32_e32 v83, v209, v83, vcc
	v_cmp_lt_u32_e32 vcc, s17, v66
	v_add_u32_e32 v66, 0xbfffff86, v216
	s_nop 0
	v_cndmask_b32_e32 v100, v209, v100, vcc
	v_cmp_lt_u32_e32 vcc, s17, v66
	v_add_u32_e32 v66, 0xbfffffa5, v216
	s_nop 0
	v_cndmask_b32_e32 v84, v209, v84, vcc
	v_cmp_lt_u32_e32 vcc, s17, v66
	v_add_u32_e32 v66, 0xbfffff85, v216
	s_nop 0
	v_cndmask_b32_e32 v101, v209, v101, vcc
	v_cmp_lt_u32_e32 vcc, s17, v66
	s_nop 1
	v_cndmask_b32_e32 v85, v209, v85, vcc

; __device__ __forceinline__ void finishSM(f32x16& p0, f32x16& p1, float alpha, float& l_reg, bf16x8& pa0, bf16x8& pa1, bf16x8& pa2, bf16x8& pa3) {
;     for (int r = 0; r < 16; ++r) p1[r] = __builtin_amdgcn_exp2f(p1[r]);
;     float ps = 0; for (int r = 0; r < 16; ++r) ps += p0[r]; for (int r = 0; r < 16; ++r) ps += p1[r];
;     { auto rr = __builtin_amdgcn_permlane32_swap(__float_as_uint(ps), __float_as_uint(ps), false, false);
;       ps = __uint_as_float(rr[0]) + __uint_as_float(rr[1]); }
;     l_reg = l_reg * alpha + ps;
;     ...
;     PK4(p0, 0, pa0); PK4(p0, 8, pa1); PK4(p1, 0, pa2); PK4(p1, 8, pa3);
;     ...
; }
; template <int KB>
; __device__ __forceinline__ void qkt(f32x16& p0, f32x16& p1, const char* K_lds, const char* cbt, int r32, int hi, const bf16x8* qr) {
;     { const u32x2 e0 = *(const u32x2*)(cbt), e1 = *(const u32x2*)(cbt + 32 * 8);
;       const unsigned c0 = hi ? 0u : 0x3F803F80u, c1 = hi ? 0u : 0x00003F80u;
;       const u32x4 k0 = {e0.x, e0.y, e0.x, e0.y}, k1 = {e1.x, e1.y, e1.x, e1.y}, q1 = {c0, c1, 0u, 0u};
;       p0 = __builtin_amdgcn_mfma_f32_32x32x16_bf16(__builtin_bit_cast(bf16x8, k0), __builtin_bit_cast(bf16x8, q1), f32x16{}, 0, 0, 0);
;       p1 = __builtin_amdgcn_mfma_f32_32x32x16_bf16(__builtin_bit_cast(bf16x8, k1), __builtin_bit_cast(bf16x8, q1), f32x16{}, 0, 0, 0); }
;     const char* kb[4];
; #pragma unroll
;     for (int dd = 0; dd < 4; ++dd) kb[dd] = K_lds + KB * SHM_K + KSWZ(r32, (dd * 16 + hi * 8) * 2);
; #pragma unroll
;     for (int d0 = 0; d0 < 8; ++d0) { const char* a = kb[d0 & 3] + (d0 >> 2) * 128;
;         bf16x8 b0 = *reinterpret_cast<const bf16x8*>(a);
;         bf16x8 b1 = *reinterpret_cast<const bf16x8*>(a + 32 * 256);
;         p0 = __builtin_amdgcn_mfma_f32_32x32x16_bf16(b0, qr[d0], p0, 0, 0, 0);
;         p1 = __builtin_amdgcn_mfma_f32_32x32x16_bf16(b1, qr[d0], p1, 0, 0, 0); }
; }
; template <int VB>
; __device__ __forceinline__ void pv_tile(f32x16* o, int vb0, bf16x8 pa0, bf16x8 pa1, bf16x8 pa2, bf16x8 pa3) {
;     ...
;     PV_R(0, 0, pa0, pa1); PV_R(0, 2, pa2, pa3); PV_R(2, 0, pa0, pa1); PV_R(2, 2, pa2, pa3);
.LBB0_238:
	ds_read_b128 v[114:117], v215 offset:0
	ds_read_b128 v[118:121], v215 offset:32
	ds_read_b128 v[122:125], v215 offset:64
	ds_read_b128 v[126:129], v215 offset:96
	ds_read_b128 v[98:101], v215 offset:128
	ds_read_b128 v[102:105], v215 offset:160
	ds_read_b128 v[106:109], v215 offset:192
	ds_read_b128 v[110:113], v215 offset:224
	v_add_f32_e32 v194, 0, v66
	v_add_f32_e32 v194, v67, v194
	v_add_f32_e32 v194, v68, v194
	v_add_f32_e32 v194, v69, v194
	v_add_f32_e32 v194, v70, v194
	v_add_f32_e32 v194, v71, v194
	v_add_f32_e32 v194, v72, v194
	v_add_f32_e32 v194, v73, v194
	v_add_f32_e32 v194, v74, v194
	v_add_f32_e32 v194, v75, v194
	v_add_f32_e32 v194, v76, v194
	ds_read_b128 v[82:85], v205 offset:32768
	ds_read_b128 v[226:229], v205 offset:40960
	v_add_f32_e32 v194, v77, v194
	v_add_f32_e32 v194, v78, v194
	v_add_f32_e32 v194, v79, v194
	v_add_f32_e32 v194, v80, v194
	v_add_f32_e32 v194, v81, v194
	v_exp_f32_e32 v87, v87
	s_waitcnt lgkmcnt(1)
	v_mfma_f32_32x32x16_bf16 v[114:129], v[82:85], v[158:161], v[114:129]
	v_exp_f32_e32 v88, v88
	v_exp_f32_e32 v89, v89
	v_exp_f32_e32 v90, v90
	v_exp_f32_e32 v91, v91
	v_exp_f32_e32 v92, v92
	v_exp_f32_e32 v93, v93
	v_exp_f32_e32 v94, v94
	s_waitcnt lgkmcnt(0)
	v_mfma_f32_32x32x16_bf16 v[98:113], v[226:229], v[158:161], v[98:113]
	ds_read_b128 v[82:85], v206 offset:32768
	ds_read_b128 v[226:229], v206 offset:40960
	s_waitcnt lgkmcnt(1)
	v_mfma_f32_32x32x16_bf16 v[114:129], v[82:85], v[154:157], v[114:129]
	s_waitcnt lgkmcnt(0)
	v_mfma_f32_32x32x16_bf16 v[98:113], v[226:229], v[154:157], v[98:113]
	ds_read_b128 v[82:85], v207 offset:32768
	ds_read_b128 v[226:229], v207 offset:40960
	s_waitcnt lgkmcnt(1)
	v_mfma_f32_32x32x16_bf16 v[114:129], v[82:85], v[150:153], v[114:129]
	s_waitcnt lgkmcnt(0)
	v_mfma_f32_32x32x16_bf16 v[98:113], v[226:229], v[150:153], v[98:113]
	ds_read_b128 v[82:85], v208 offset:32768
	ds_read_b128 v[226:229], v208 offset:40960
	s_waitcnt lgkmcnt(1)
	v_mfma_f32_32x32x16_bf16 v[114:129], v[82:85], v[146:149], v[114:129]
	s_waitcnt lgkmcnt(0)
	v_mfma_f32_32x32x16_bf16 v[98:113], v[226:229], v[146:149], v[98:113]
	ds_read_b128 v[82:85], v205 offset:32896
	ds_read_b128 v[226:229], v205 offset:41088
	s_waitcnt lgkmcnt(1)
	v_mfma_f32_32x32x16_bf16 v[114:129], v[82:85], v[142:145], v[114:129]
	s_waitcnt lgkmcnt(0)
	v_mfma_f32_32x32x16_bf16 v[98:113], v[226:229], v[142:145], v[98:113]
	ds_read_b128 v[82:85], v206 offset:32896
	ds_read_b128 v[226:229], v206 offset:41088
	s_waitcnt lgkmcnt(1)
	v_mfma_f32_32x32x16_bf16 v[114:129], v[82:85], v[138:141], v[114:129]
	s_waitcnt lgkmcnt(0)
	v_mfma_f32_32x32x16_bf16 v[98:113], v[226:229], v[138:141], v[98:113]
	ds_read_b128 v[82:85], v207 offset:32896
	ds_read_b128 v[226:229], v207 offset:41088
	s_waitcnt lgkmcnt(1)
	v_mfma_f32_32x32x16_bf16 v[114:129], v[82:85], v[134:137], v[114:129]
	s_waitcnt lgkmcnt(0)
	v_mfma_f32_32x32x16_bf16 v[98:113], v[226:229], v[134:137], v[98:113]
	ds_read_b128 v[82:85], v208 offset:32896
	ds_read_b128 v[226:229], v208 offset:41088
	s_waitcnt lgkmcnt(1)
	v_mfma_f32_32x32x16_bf16 v[114:129], v[82:85], v[130:133], v[114:129]
	v_exp_f32_e32 v82, v86
	v_exp_f32_e32 v83, v95
	v_exp_f32_e32 v84, v96
	v_exp_f32_e32 v85, v97
	v_exp_f32_e32 v86, v222
	v_add_f32_e32 v194, v82, v194
	v_add_f32_e32 v194, v83, v194
	v_add_f32_e32 v194, v84, v194
	v_add_f32_e32 v194, v85, v194
	v_add_f32_e32 v194, v86, v194
	v_add_f32_e32 v194, v87, v194
	v_add_f32_e32 v194, v88, v194
	v_add_f32_e32 v194, v89, v194
	v_add_f32_e32 v194, v90, v194
	v_exp_f32_e32 v95, v223
	v_add_f32_e32 v194, v91, v194
	s_waitcnt lgkmcnt(0)
	v_mfma_f32_32x32x16_bf16 v[98:113], v[226:229], v[130:133], v[98:113]
	v_exp_f32_e32 v96, v224
	v_add_f32_e32 v194, v92, v194
	v_exp_f32_e32 v97, v221
	v_add_f32_e32 v194, v93, v194
	v_add_f32_e32 v194, v94, v194
	v_add_f32_e32 v194, v95, v194
	v_add_f32_e32 v194, v96, v194
	v_add_f32_e32 v237, v97, v194
	v_mov_b32_e32 v238, v237
	s_nop 1
	v_permlane32_swap_b32_e32 v237, v238
	v_cvt_pk_bf16_f32 v222, v66, v67
	v_cvt_pk_bf16_f32 v223, v68, v69
	v_cvt_pk_bf16_f32 v224, v70, v71
	v_cvt_pk_bf16_f32 v225, v72, v73
	v_cvt_pk_bf16_f32 v226, v74, v75
	v_cvt_pk_bf16_f32 v227, v76, v77
	v_cvt_pk_bf16_f32 v228, v78, v79
	v_cvt_pk_bf16_f32 v229, v80, v81
	v_cvt_pk_bf16_f32 v230, v82, v83
	v_cvt_pk_bf16_f32 v231, v84, v85
	v_cvt_pk_bf16_f32 v232, v86, v87
	v_cvt_pk_bf16_f32 v233, v88, v89
	v_cvt_pk_bf16_f32 v240, v90, v91
	v_cvt_pk_bf16_f32 v241, v92, v93
	v_cvt_pk_bf16_f32 v242, v94, v95
	v_cvt_pk_bf16_f32 v243, v96, v97
	s_nop 0
	v_permlane32_swap_b32_e32 v222, v224
	v_permlane32_swap_b32_e32 v223, v225
	v_permlane32_swap_b32_e32 v226, v228
	v_permlane32_swap_b32_e32 v227, v229
	v_permlane32_swap_b32_e32 v230, v232
	v_permlane32_swap_b32_e32 v231, v233
	v_permlane32_swap_b32_e32 v240, v242
	v_permlane32_swap_b32_e32 v241, v243
	ds_read_b64_tr_b16 v[244:245], v199 offset:0x4000
	ds_read_b64_tr_b16 v[246:247], v199 offset:0x4800
	ds_read_b64_tr_b16 v[248:249], v199 offset:0x4200
	ds_read_b64_tr_b16 v[250:251], v199 offset:0x4a00
	ds_read_b64_tr_b16 v[252:253], v199 offset:0x5000
	ds_read_b64_tr_b16 v[254:255], v199 offset:0x5800
	ds_read_b64_tr_b16 v[194:195], v199 offset:0x5200
	ds_read_b64_tr_b16 v[196:197], v199 offset:0x5a00
	s_waitcnt lgkmcnt(0)
	s_nop 0
	v_mfma_f32_32x32x16_bf16 v[50:65], v[222:225], v[248:251], v[50:65]
	v_mfma_f32_32x32x16_bf16 v[2:17], v[222:225], v[244:247], v[2:17]
	v_mfma_f32_32x32x16_bf16 v[50:65], v[226:229], v[194:197], v[50:65]
	ds_read_b64_tr_b16 v[194:195], v199 offset:0x6000
	ds_read_b64_tr_b16 v[196:197], v199 offset:0x6800
	ds_read_b64_tr_b16 v[244:245], v199 offset:0x6200
	ds_read_b64_tr_b16 v[246:247], v199 offset:0x6a00
	ds_read_b64_tr_b16 v[248:249], v199 offset:0x7000
	ds_read_b64_tr_b16 v[250:251], v199 offset:0x7800
	v_mfma_f32_32x32x16_bf16 v[2:17], v[226:229], v[252:255], v[2:17]
	ds_read_b64_tr_b16 v[252:253], v199 offset:0x7200
	ds_read_b64_tr_b16 v[254:255], v199 offset:0x7a00
	s_waitcnt lgkmcnt(0)
; __device__ __forceinline__ void mask_tile(f32x16& p0, f32x16& p1, int dq, unsigned W) {
;     const float NEG = -__builtin_inff();
; #pragma unroll
;     for (int r = 0; r < 16; ++r) {
;         const int c = (r & 3) + 8 * (r >> 2);
;         if ((unsigned)(dq - c) >= W) p0[r] = NEG;
;         if ((unsigned)(dq - c - 32) >= W) p1[r] = NEG;
;     }
; }
; template <int VB>
; __device__ __forceinline__ void pv_tile(f32x16* o, int vb0, bf16x8 pa0, bf16x8 pa1, bf16x8 pa2, bf16x8 pa3) {
;     ...
;     PV_R(0, 0, pa0, pa1); PV_R(0, 2, pa2, pa3); PV_R(2, 0, pa0, pa1); PV_R(2, 2, pa2, pa3);
	v_mfma_f32_32x32x16_bf16 v[2:17], v[230:233], v[194:197], v[2:17]
	ds_read_b64_tr_b16 v[194:195], v199 offset:0x4400
	ds_read_b64_tr_b16 v[196:197], v199 offset:0x4c00
	v_mfma_f32_32x32x16_bf16 v[50:65], v[230:233], v[244:247], v[50:65]
	ds_read_b64_tr_b16 v[244:245], v199 offset:0x4600
	ds_read_b64_tr_b16 v[246:247], v199 offset:0x4e00
	v_mfma_f32_32x32x16_bf16 v[2:17], v[240:243], v[248:251], v[2:17]
	ds_read_b64_tr_b16 v[248:249], v199 offset:0x5400
	ds_read_b64_tr_b16 v[250:251], v199 offset:0x5c00
	v_mfma_f32_32x32x16_bf16 v[50:65], v[240:243], v[252:255], v[50:65]
	ds_read_b64_tr_b16 v[252:253], v199 offset:0x5600
	ds_read_b64_tr_b16 v[254:255], v199 offset:0x5e00
	s_waitcnt lgkmcnt(0)
	v_mfma_f32_32x32x16_bf16 v[34:49], v[222:225], v[194:197], v[34:49]
	ds_read_b64_tr_b16 v[194:195], v199 offset:0x6400
	ds_read_b64_tr_b16 v[196:197], v199 offset:0x6c00
	v_mfma_f32_32x32x16_bf16 v[18:33], v[222:225], v[244:247], v[18:33]
	ds_read_b64_tr_b16 v[222:223], v199 offset:0x6600
	ds_read_b64_tr_b16 v[224:225], v199 offset:0x6e00
	ds_read_b64_tr_b16 v[244:245], v199 offset:0x7400
	ds_read_b64_tr_b16 v[246:247], v199 offset:0x7c00
	v_mfma_f32_32x32x16_bf16 v[34:49], v[226:229], v[248:251], v[34:49]
	ds_read_b64_tr_b16 v[248:249], v199 offset:0x7600
	ds_read_b64_tr_b16 v[250:251], v199 offset:0x7e00
	s_waitcnt lgkmcnt(0)
	v_mfma_f32_32x32x16_bf16 v[18:33], v[226:229], v[252:255], v[18:33]
	v_mfma_f32_32x32x16_bf16 v[34:49], v[230:233], v[194:197], v[34:49]
	s_sub_i32 s4, s89, 64
	s_cmp_le_i32 s4, s76
	v_mfma_f32_32x32x16_bf16 v[18:33], v[230:233], v[222:225], v[18:33]
	v_mfma_f32_32x32x16_bf16 v[34:49], v[240:243], v[244:247], v[34:49]
	v_mfma_f32_32x32x16_bf16 v[18:33], v[240:243], v[248:251], v[18:33]
	s_cbranch_scc1 .LBB0_240
	v_cmp_gt_u32_e32 vcc, 2.0, v216
	v_add_u32_e32 v194, 0xbfffffe0, v216
	s_nop 0
	v_cndmask_b32_e32 v114, v209, v114, vcc
	v_cmp_lt_u32_e32 vcc, s17, v194
	v_add_u32_e32 v194, 0xbfffffff, v216
	s_nop 0
	v_cndmask_b32_e32 v98, v209, v98, vcc
	v_cmp_lt_u32_e32 vcc, s17, v194
	v_add_u32_e32 v194, 0xbfffffdf, v216
	s_nop 0
	v_cndmask_b32_e32 v115, v209, v115, vcc
	v_cmp_lt_u32_e32 vcc, s17, v194
	v_add_u32_e32 v194, 0xbffffffe, v216
	s_nop 0
	v_cndmask_b32_e32 v99, v209, v99, vcc
	v_cmp_lt_u32_e32 vcc, s17, v194
	v_add_u32_e32 v194, 0xbfffffde, v216
	s_nop 0
	v_cndmask_b32_e32 v116, v209, v116, vcc
	v_cmp_lt_u32_e32 vcc, s17, v194
	v_add_u32_e32 v194, 0xbffffffd, v216
	s_nop 0
	v_cndmask_b32_e32 v100, v209, v100, vcc
	v_cmp_lt_u32_e32 vcc, s17, v194
	v_add_u32_e32 v194, 0xbfffffdd, v216
	s_nop 0
	v_cndmask_b32_e32 v117, v209, v117, vcc
	v_cmp_lt_u32_e32 vcc, s17, v194
	v_add_u32_e32 v194, 0xbffffff8, v216
	s_nop 0
	v_cndmask_b32_e32 v101, v209, v101, vcc
	v_cmp_lt_u32_e32 vcc, s17, v194
	v_add_u32_e32 v194, 0xbfffffd8, v216
	s_nop 0
	v_cndmask_b32_e32 v118, v209, v118, vcc
	v_cmp_lt_u32_e32 vcc, s17, v194
	v_add_u32_e32 v194, 0xbffffff7, v216
	s_nop 0
	v_cndmask_b32_e32 v102, v209, v102, vcc
	v_cmp_lt_u32_e32 vcc, s17, v194
	v_add_u32_e32 v194, 0xbfffffd7, v216
	s_nop 0
	v_cndmask_b32_e32 v119, v209, v119, vcc
	v_cmp_lt_u32_e32 vcc, s17, v194
	v_add_u32_e32 v194, 0xbffffff6, v216
	s_nop 0
	v_cndmask_b32_e32 v103, v209, v103, vcc
	v_cmp_lt_u32_e32 vcc, s17, v194
	v_add_u32_e32 v194, 0xbfffffd6, v216
	s_nop 0
	v_cndmask_b32_e32 v120, v209, v120, vcc
	v_cmp_lt_u32_e32 vcc, s17, v194
	v_add_u32_e32 v194, 0xbffffff5, v216
	s_nop 0
	v_cndmask_b32_e32 v104, v209, v104, vcc
	v_cmp_lt_u32_e32 vcc, s17, v194
	v_add_u32_e32 v194, 0xbfffffd5, v216
	s_nop 0
	v_cndmask_b32_e32 v121, v209, v121, vcc
	v_cmp_lt_u32_e32 vcc, s17, v194
	v_add_u32_e32 v194, 0xbffffff0, v216
	s_nop 0
	v_cndmask_b32_e32 v105, v209, v105, vcc
	v_cmp_lt_u32_e32 vcc, s17, v194
	v_add_u32_e32 v194, 0xbfffffd0, v216
	s_nop 0
	v_cndmask_b32_e32 v122, v209, v122, vcc
	v_cmp_lt_u32_e32 vcc, s17, v194
	v_add_u32_e32 v194, 0xbfffffef, v216
	s_nop 0
	v_cndmask_b32_e32 v106, v209, v106, vcc
	v_cmp_lt_u32_e32 vcc, s17, v194
	v_add_u32_e32 v194, 0xbfffffcf, v216
	s_nop 0
	v_cndmask_b32_e32 v123, v209, v123, vcc
	v_cmp_lt_u32_e32 vcc, s17, v194
	v_add_u32_e32 v194, 0xbfffffee, v216
	s_nop 0
	v_cndmask_b32_e32 v107, v209, v107, vcc
	v_cmp_lt_u32_e32 vcc, s17, v194
	v_add_u32_e32 v194, 0xbfffffce, v216
	s_nop 0
	v_cndmask_b32_e32 v124, v209, v124, vcc
	v_cmp_lt_u32_e32 vcc, s17, v194
	v_add_u32_e32 v194, 0xbfffffed, v216
	s_nop 0
	v_cndmask_b32_e32 v108, v209, v108, vcc
	v_cmp_lt_u32_e32 vcc, s17, v194
	v_add_u32_e32 v194, 0xbfffffcd, v216
	s_nop 0
	v_cndmask_b32_e32 v125, v209, v125, vcc
	v_cmp_lt_u32_e32 vcc, s17, v194
	v_add_u32_e32 v194, 0xbfffffe8, v216
	s_nop 0
	v_cndmask_b32_e32 v109, v209, v109, vcc
	v_cmp_lt_u32_e32 vcc, s17, v194
	v_add_u32_e32 v194, 0xbfffffc8, v216
	s_nop 0
	v_cndmask_b32_e32 v126, v209, v126, vcc
	v_cmp_lt_u32_e32 vcc, s17, v194
	v_add_u32_e32 v194, 0xbfffffe7, v216
	s_nop 0
	v_cndmask_b32_e32 v110, v209, v110, vcc
	v_cmp_lt_u32_e32 vcc, s17, v194
	v_add_u32_e32 v194, 0xbfffffc7, v216
	s_nop 0
	v_cndmask_b32_e32 v127, v209, v127, vcc
	v_cmp_lt_u32_e32 vcc, s17, v194
	v_add_u32_e32 v194, 0xbfffffe6, v216
	s_nop 0
	v_cndmask_b32_e32 v111, v209, v111, vcc
	v_cmp_lt_u32_e32 vcc, s17, v194
	v_add_u32_e32 v194, 0xbfffffc6, v216
	s_nop 0
	v_cndmask_b32_e32 v128, v209, v128, vcc
	v_cmp_lt_u32_e32 vcc, s17, v194
	v_add_u32_e32 v194, 0xbfffffe5, v216
	s_nop 0
	v_cndmask_b32_e32 v112, v209, v112, vcc
	v_cmp_lt_u32_e32 vcc, s17, v194
	v_add_u32_e32 v194, 0xbfffffc5, v216
	s_nop 0
	v_cndmask_b32_e32 v129, v209, v129, vcc
	v_cmp_lt_u32_e32 vcc, s17, v194
	s_nop 1
	v_cndmask_b32_e32 v113, v209, v113, vcc

; __device__ __forceinline__ void partialSM(f32x16& p0, f32x16& p1, float& m_reg, float& mn, float& alpha) {
;     ...
;     const float mnL = -mn * C2;
;     for (int r = 0; r < 16; ++r) p0[r] = fmaf(p0[r], C2, mnL); for (int r = 0; r < 16; ++r) p1[r] = fmaf(p1[r], C2, mnL);
;     for (int r = 0; r < 16; ++r) p0[r] = __builtin_amdgcn_exp2f(p0[r]);
; }
; __device__ __forceinline__ void finishSM(f32x16& p0, f32x16& p1, float alpha, float& l_reg, bf16x8& pa0, bf16x8& pa1, bf16x8& pa2, bf16x8& pa3) {
;     for (int r = 0; r < 16; ++r) p1[r] = __builtin_amdgcn_exp2f(p1[r]);
;     float ps = 0; for (int r = 0; r < 16; ++r) ps += p0[r]; for (int r = 0; r < 16; ++r) ps += p1[r];
;     { auto rr = __builtin_amdgcn_permlane32_swap(__float_as_uint(ps), __float_as_uint(ps), false, false);
;       ps = __uint_as_float(rr[0]) + __uint_as_float(rr[1]); }
;     l_reg = l_reg * alpha + ps;
; template <int KB>
; __device__ __forceinline__ void qkt(f32x16& p0, f32x16& p1, const char* K_lds, const char* cbt, int r32, int hi, const bf16x8* qr) {
;     { const u32x2 e0 = *(const u32x2*)(cbt), e1 = *(const u32x2*)(cbt + 32 * 8);
;       const unsigned c0 = hi ? 0u : 0x3F803F80u, c1 = hi ? 0u : 0x00003F80u;
;       const u32x4 k0 = {e0.x, e0.y, e0.x, e0.y}, k1 = {e1.x, e1.y, e1.x, e1.y}, q1 = {c0, c1, 0u, 0u};
;       p0 = __builtin_amdgcn_mfma_f32_32x32x16_bf16(__builtin_bit_cast(bf16x8, k0), __builtin_bit_cast(bf16x8, q1), f32x16{}, 0, 0, 0);
;       p1 = __builtin_amdgcn_mfma_f32_32x32x16_bf16(__builtin_bit_cast(bf16x8, k1), __builtin_bit_cast(bf16x8, q1), f32x16{}, 0, 0, 0); }
;     const char* kb[4];
; #pragma unroll
;     for (int dd = 0; dd < 4; ++dd) kb[dd] = K_lds + KB * SHM_K + KSWZ(r32, (dd * 16 + hi * 8) * 2);
; #pragma unroll
;     for (int d0 = 0; d0 < 8; ++d0) { const char* a = kb[d0 & 3] + (d0 >> 2) * 128;
;         bf16x8 b0 = *reinterpret_cast<const bf16x8*>(a);
;         bf16x8 b1 = *reinterpret_cast<const bf16x8*>(a + 32 * 256);
;         p0 = __builtin_amdgcn_mfma_f32_32x32x16_bf16(b0, qr[d0], p0, 0, 0, 0);
;         p1 = __builtin_amdgcn_mfma_f32_32x32x16_bf16(b1, qr[d0], p1, 0, 0, 0); }
; }
.LBB0_246:
	v_cndmask_b32_e64 v217, v167, v217, s[4:5]
	v_mul_f32_e32 v168, 0xbe0293ee, v217
	s_waitcnt vmcnt(0)
	v_mov_b32_e32 v178, v168
	v_fmamk_f32 v167, v114, 0x3e0293ee, v168
	v_fmamk_f32 v169, v115, 0x3e0293ee, v168
	v_fmamk_f32 v170, v116, 0x3e0293ee, v168
	v_fmamk_f32 v171, v117, 0x3e0293ee, v168
	v_fmamk_f32 v118, v118, 0x3e0293ee, v168
	v_fmamk_f32 v119, v119, 0x3e0293ee, v168
	v_fmamk_f32 v172, v120, 0x3e0293ee, v168
	v_fmamk_f32 v173, v121, 0x3e0293ee, v168
	v_fmamk_f32 v122, v122, 0x3e0293ee, v168
	v_fmamk_f32 v123, v123, 0x3e0293ee, v168
	v_fmamk_f32 v174, v124, 0x3e0293ee, v168
	v_fmamk_f32 v175, v125, 0x3e0293ee, v168
	v_fmamk_f32 v176, v126, 0x3e0293ee, v168
	v_fmamk_f32 v177, v127, 0x3e0293ee, v168
	v_fmamk_f32 v128, v128, 0x3e0293ee, v168
	v_fmac_f32_e32 v178, 0x3e0293ee, v129
	v_exp_f32_e32 v234, v167
	v_exp_f32_e32 v236, v169
	v_exp_f32_e32 v232, v170
	v_exp_f32_e32 v235, v171
	v_exp_f32_e32 v231, v118
	v_exp_f32_e32 v233, v119
	v_exp_f32_e32 v229, v172
	v_exp_f32_e32 v230, v173
	v_exp_f32_e32 v226, v122
	v_exp_f32_e32 v228, v123
	v_exp_f32_e32 v225, v174
	v_exp_f32_e32 v227, v175
	v_exp_f32_e32 v222, v176
	v_exp_f32_e32 v224, v177
	v_exp_f32_e32 v221, v128
	v_exp_f32_e32 v223, v178
	v_pk_fma_f32 v[126:127], v[98:99], s[16:17], v[168:169] op_sel_hi:[1,0,0]
	v_add_f32_e32 v98, v218, v219
	v_fmac_f32_e32 v98, v187, v214
	v_add_f32_e32 v214, v237, v238
	s_addk_i32 s89, 0xff80
	s_add_i32 s85, s85, 2
	v_pk_fma_f32 v[124:125], v[100:101], s[16:17], v[168:169] op_sel_hi:[1,0,0]
	v_pk_fma_f32 v[120:121], v[102:103], s[16:17], v[168:169] op_sel_hi:[1,0,0]
	v_pk_fma_f32 v[116:117], v[104:105], s[16:17], v[168:169] op_sel_hi:[1,0,0]
	v_pk_fma_f32 v[114:115], v[106:107], s[16:17], v[168:169] op_sel_hi:[1,0,0]
	v_pk_fma_f32 v[128:129], v[108:109], s[16:17], v[168:169] op_sel_hi:[1,0,0]
	v_pk_fma_f32 v[122:123], v[110:111], s[16:17], v[168:169] op_sel_hi:[1,0,0]
	v_pk_fma_f32 v[118:119], v[112:113], s[16:17], v[168:169] op_sel_hi:[1,0,0]
	v_fmac_f32_e32 v214, v98, v220
	v_add_u32_e32 v215, 0xfffffe00, v215
	s_cmp_ge_u32 s85, s77
	v_add_u32_e32 v216, 0x80, v216
	s_waitcnt lgkmcnt(0)
	s_barrier
	s_cbranch_scc1 .LBB0_248
	v_mov_b32_e32 v187, v166
	s_branch .LBB0_230
.LBB0_248:
	v_lshlrev_b32_e32 v184, 4, v0
	v_and_b32_e32 v182, 0xf0, v184
	v_mov_b32_e32 v183, 0
	v_mov_b32_e32 v185, 0
	v_and_b32_e32 v1, 31, v0
	v_and_b32_e32 v201, 63, v0
	s_bitcmp0_b32 s84, 6
	s_cselect_b64 s[4:5], -1, 0
	s_and_b64 vcc, exec, s[4:5]
	s_cbranch_vccz .LBB0_250
	ds_read_b128 v[66:69], v200 offset:0
	ds_read_b128 v[70:73], v200 offset:32
	ds_read_b128 v[74:77], v200 offset:64
	ds_read_b128 v[78:81], v200 offset:96
	ds_read_b128 v[82:85], v200 offset:128
	ds_read_b128 v[86:89], v200 offset:160
	ds_read_b128 v[90:93], v200 offset:192
	ds_read_b128 v[94:97], v200 offset:224
	ds_read_b128 v[98:101], v205 offset:49152
	ds_read_b128 v[102:105], v205 offset:49280
	s_waitcnt lgkmcnt(1)
	v_mfma_f32_32x32x16_bf16 v[66:81], v[98:101], v[158:161], v[66:81]
	ds_read_b128 v[98:101], v205 offset:57344
	ds_read_b128 v[106:109], v205 offset:57472
	s_waitcnt lgkmcnt(1)
	v_mfma_f32_32x32x16_bf16 v[82:97], v[98:101], v[158:161], v[82:97]
	ds_read_b128 v[98:101], v206 offset:49152
	ds_read_b128 v[110:113], v206 offset:49280
	s_waitcnt lgkmcnt(1)
	v_mfma_f32_32x32x16_bf16 v[66:81], v[98:101], v[154:157], v[66:81]
	ds_read_b128 v[98:101], v206 offset:57344
	ds_read_b128 v[158:161], v206 offset:57472
	s_waitcnt lgkmcnt(1)
	v_mfma_f32_32x32x16_bf16 v[82:97], v[98:101], v[154:157], v[82:97]
	ds_read_b128 v[98:101], v207 offset:49152
	ds_read_b128 v[154:157], v207 offset:49280
	s_waitcnt lgkmcnt(1)
	v_mfma_f32_32x32x16_bf16 v[66:81], v[98:101], v[150:153], v[66:81]
	ds_read_b128 v[98:101], v207 offset:57344
	ds_read_b128 v[168:171], v207 offset:57472
	s_waitcnt lgkmcnt(1)
	v_mfma_f32_32x32x16_bf16 v[82:97], v[98:101], v[150:153], v[82:97]
	ds_read_b128 v[98:101], v208 offset:49152
	ds_read_b128 v[150:153], v208 offset:49280
	s_waitcnt lgkmcnt(1)
	v_mfma_f32_32x32x16_bf16 v[66:81], v[98:101], v[146:149], v[66:81]
	ds_read_b128 v[98:101], v208 offset:57344
	ds_read_b128 v[172:175], v208 offset:57472
	s_waitcnt lgkmcnt(1)
	v_mfma_f32_32x32x16_bf16 v[82:97], v[98:101], v[146:149], v[82:97]
	v_mfma_f32_32x32x16_bf16 v[66:81], v[102:105], v[142:145], v[66:81]
	v_mfma_f32_32x32x16_bf16 v[82:97], v[106:109], v[142:145], v[82:97]
	v_mfma_f32_32x32x16_bf16 v[66:81], v[110:113], v[138:141], v[66:81]
	v_mfma_f32_32x32x16_bf16 v[82:97], v[158:161], v[138:141], v[82:97]
	v_mfma_f32_32x32x16_bf16 v[66:81], v[154:157], v[134:137], v[66:81]
	v_mfma_f32_32x32x16_bf16 v[82:97], v[168:171], v[134:137], v[82:97]
	v_mfma_f32_32x32x16_bf16 v[66:81], v[150:153], v[130:133], v[66:81]
	s_waitcnt lgkmcnt(0)
	v_mfma_f32_32x32x16_bf16 v[82:97], v[172:175], v[130:133], v[82:97]

; #define SBAR() __builtin_amdgcn_sched_barrier(0)
; __device__ __forceinline__ int crow(int r, int hi) { return (r & 3) + 8 * (r >> 2) + 4 * hi; }
; __device__ __forceinline__ unsigned cvtpk(float lo, float hi) { unsigned r; asm volatile("v_cvt_pk_bf16_f32 %0, %1, %2" : "=v"(r) : "v"(lo), "v"(hi)); return r; }
; #define SEAM_K0() do { VMWN(NQL); SWRITE_HK(0); SBAR(); } while (0)
; __device__ __forceinline__ void fox_block(const BlockRef& cur, const BlockRef& nxt, char* lds, char* cbcur, char* cbnxt, Seam& S) {
;     ...
;     SBAR(); SEAM_K0();
;     if (hi == 0) li_l[r32] = l_reg; asm volatile("s_waitcnt lgkmcnt(0)" ::: "memory");
;     float rli[16];
; #pragma unroll
;     for (int r = 0; r < 16; ++r) rli[r] = __builtin_amdgcn_rcpf(li_l[crow(r, hi)]);
;     {
;         int ln = lane; asm volatile("" : "+v"(ln)); const int r32e = ln & 31, hie = ln >> 5;
;         char* stg = lds + LDS_STG_OFF + wid * 4352;
;         bf16* Ow = cur.O + (size_t)(wid * QBLK) * QP; const bf16* Zw = cur.Z + (size_t)(wid * QBLK) * ZP;
; #pragma unroll
;         for (int half = 0; half < 2; ++half) {
; #pragma unroll
;             for (int rr = 0; rr < 8; ++rr) { const int r = half * 8 + rr; const int lrow = (rr & 3) + 8 * (rr >> 2) + 4 * hie;
; #pragma unroll
;                 for (int d0 = 0; d0 < 4; ++d0) *(unsigned short*)(stg + lrow * 272 + (d0 * 32 + r32e) * 2) = (unsigned short)cvtpk(o[d0][r] * rli[r], 0.f); }
.LBB0_258:
	v_mov_b32_e32 v66, v0
	s_waitcnt vmcnt(8)
	s_nop 0
	v_lshlrev_b32_e32 v67, 4, v66
	v_and_b32_e32 v66, 0x70, v66
	v_and_b32_e32 v68, 0xffffff00, v67
	v_bitop3_b32 v66, v67, v66, s79 bitop3:0x6c
	v_add3_u32 v66, 0, v68, v66
	s_waitcnt vmcnt(9)
	ds_write_b128 v66, v[106:109] offset:32768
	s_waitcnt vmcnt(8)
	ds_write_b128 v66, v[110:113] offset:40960
	s_and_saveexec_b64 s[4:5], s[6:7]
	ds_write_b32 v212, v114
	s_or_b64 exec, exec, s[4:5]
	s_waitcnt lgkmcnt(0)
	ds_read_b128 v[66:69], v211
	ds_read_b128 v[70:73], v211 offset:32
	s_mulk_i32 s69, 0x1100
	s_add_i32 s4, s69, 0
	s_add_i32 s69, s4, 0x18800
	s_waitcnt lgkmcnt(1)
	v_rcp_f32_e32 v77, v66
	s_lshl_b64 s[4:5], s[14:15], 12
	v_rcp_f32_e32 v81, v67
	v_mov_b32_e32 v74, v201
	s_add_u32 s4, s70, s4
	v_rcp_f32_e32 v84, v68
	v_rcp_f32_e32 v85, v69
	s_waitcnt lgkmcnt(0)
	v_rcp_f32_e32 v86, v70
	v_rcp_f32_e32 v87, v71
	v_rcp_f32_e32 v88, v72
	v_rcp_f32_e32 v89, v73
	ds_read_b128 v[66:69], v211 offset:64
	ds_read_b128 v[70:73], v211 offset:96
	s_addc_u32 s5, s71, s5
	s_lshl_b64 s[70:71], s[14:15], 11
	v_lshlrev_b32_e32 v75, 1, v74
	s_add_u32 s70, s72, s70
	v_ashrrev_i32_e32 v90, 3, v74
	v_and_b32_e32 v75, 62, v75
	v_ashrrev_i32_e32 v76, 4, v74
	v_lshlrev_b32_e32 v74, 4, v74
	s_addc_u32 s71, s73, s71
	v_and_b32_e32 v78, 0xffffffc, v90
	v_add_u32_e32 v80, s69, v75
	v_and_b32_e32 v82, 0xf0, v74
	v_mov_b32_e32 v83, v183
	v_mul_f32_e32 v2, v2, v77
	v_lshl_add_u64 v[74:75], s[70:71], 0, v[82:83]
	v_lshlrev_b32_e32 v216, 11, v76
	v_mov_b32_e32 v217, 0
	v_lshl_add_u64 v[214:215], v[74:75], 0, v[216:217]
	v_mov_b32_e32 v216, 0x2000
	global_load_dwordx4 v[166:169], v[214:215], off
	v_lshl_add_u64 v[214:215], v[214:215], 0, v[216:217]
	global_load_dwordx4 v[170:173], v[214:215], off
	v_lshl_add_u64 v[214:215], v[214:215], 0, v[216:217]
	global_load_dwordx4 v[174:177], v[214:215], off
	v_lshl_add_u64 v[214:215], v[214:215], 0, v[216:217]
	global_load_dwordx4 v[178:181], v[214:215], off
	v_lshl_add_u64 v[214:215], v[214:215], 0, v[216:217]
	global_load_dwordx4 v[240:243], v[214:215], off
	v_lshl_add_u64 v[214:215], v[214:215], 0, v[216:217]
	global_load_dwordx4 v[244:247], v[214:215], off
	v_lshl_add_u64 v[214:215], v[214:215], 0, v[216:217]
	global_load_dwordx4 v[248:251], v[214:215], off
	v_lshl_add_u64 v[214:215], v[214:215], 0, v[216:217]
	global_load_dwordx4 v[252:255], v[214:215], off
	v_mad_u64_u32 v[78:79], s[70:71], v78, s80, v[80:81]
	v_cvt_pk_bf16_f32 v2, v2, v183
	ds_write_b16 v78, v2
	v_mul_f32_e32 v2, v50, v77
	v_cvt_pk_bf16_f32 v2, v2, v183
	ds_write_b16 v78, v2 offset:64
	v_mul_f32_e32 v2, v34, v77
	v_cvt_pk_bf16_f32 v2, v2, v183
	ds_write_b16 v78, v2 offset:128
	v_mul_f32_e32 v2, v18, v77
	v_cvt_pk_bf16_f32 v2, v2, v183
	ds_write_b16 v78, v2 offset:192
	v_mul_f32_e32 v2, v3, v81
	v_cvt_pk_bf16_f32 v2, v2, v183
	ds_write_b16 v78, v2 offset:272
	v_mul_f32_e32 v2, v51, v81
	v_cvt_pk_bf16_f32 v2, v2, v183
	ds_write_b16 v78, v2 offset:336
	v_mul_f32_e32 v2, v35, v81
	v_cvt_pk_bf16_f32 v2, v2, v183
	ds_write_b16 v78, v2 offset:400
	v_mul_f32_e32 v2, v19, v81
	v_cvt_pk_bf16_f32 v2, v2, v183
	ds_write_b16 v78, v2 offset:464
	v_mul_f32_e32 v2, v4, v84
	v_cvt_pk_bf16_f32 v2, v2, v183
	ds_write_b16 v78, v2 offset:544
	v_mul_f32_e32 v2, v52, v84
	v_cvt_pk_bf16_f32 v2, v2, v183
	ds_write_b16 v78, v2 offset:608
	v_mul_f32_e32 v2, v36, v84
	v_cvt_pk_bf16_f32 v2, v2, v183
	ds_write_b16 v78, v2 offset:672
	v_mul_f32_e32 v2, v20, v84
	v_cvt_pk_bf16_f32 v2, v2, v183
	ds_write_b16 v78, v2 offset:736
	v_or_b32_e32 v2, 3, v90
	v_mad_u64_u32 v[18:19], s[70:71], v2, s80, v[80:81]
	v_mul_f32_e32 v2, v5, v85
	v_cvt_pk_bf16_f32 v2, v2, v183
	ds_write_b16 v18, v2
	v_mul_f32_e32 v2, v53, v85
	v_cvt_pk_bf16_f32 v2, v2, v183
	ds_write_b16 v18, v2 offset:64
	v_mul_f32_e32 v2, v37, v85
	v_cvt_pk_bf16_f32 v2, v2, v183
	ds_write_b16 v18, v2 offset:128
	v_mul_f32_e32 v2, v21, v85
	v_cvt_pk_bf16_f32 v2, v2, v183
	ds_write_b16 v18, v2 offset:192
	v_mul_f32_e32 v2, v6, v86
	v_cvt_pk_bf16_f32 v2, v2, v183
	ds_write_b16 v78, v2 offset:2176
	v_mul_f32_e32 v2, v54, v86
	v_cvt_pk_bf16_f32 v2, v2, v183
	ds_write_b16 v78, v2 offset:2240
	v_mul_f32_e32 v2, v38, v86
	v_cvt_pk_bf16_f32 v2, v2, v183
	ds_write_b16 v78, v2 offset:2304
	v_mul_f32_e32 v2, v22, v86
	v_cvt_pk_bf16_f32 v2, v2, v183
	ds_write_b16 v78, v2 offset:2368
	v_mul_f32_e32 v2, v7, v87
	v_cvt_pk_bf16_f32 v2, v2, v183
	ds_write_b16 v78, v2 offset:2448
	v_mul_f32_e32 v2, v55, v87
	v_cvt_pk_bf16_f32 v2, v2, v183
	ds_write_b16 v78, v2 offset:2512
	v_mul_f32_e32 v2, v39, v87
	v_cvt_pk_bf16_f32 v2, v2, v183
	ds_write_b16 v78, v2 offset:2576
	v_mul_f32_e32 v2, v23, v87
	v_cvt_pk_bf16_f32 v2, v2, v183
	ds_write_b16 v78, v2 offset:2640
	v_mul_f32_e32 v2, v8, v88
	v_cvt_pk_bf16_f32 v2, v2, v183
	ds_write_b16 v78, v2 offset:2720
	v_mul_f32_e32 v2, v56, v88
	v_cvt_pk_bf16_f32 v2, v2, v183
	ds_write_b16 v78, v2 offset:2784
	v_mul_f32_e32 v2, v40, v88
	v_cvt_pk_bf16_f32 v2, v2, v183
	ds_write_b16 v78, v2 offset:2848
	v_mul_f32_e32 v2, v24, v88
	v_cvt_pk_bf16_f32 v2, v2, v183
	ds_write_b16 v78, v2 offset:2912
	v_mul_f32_e32 v2, v9, v89
	v_cvt_pk_bf16_f32 v2, v2, v183
	ds_write_b16 v18, v2 offset:2176
	v_mul_f32_e32 v2, v57, v89
	v_cvt_pk_bf16_f32 v2, v2, v183
	ds_write_b16 v18, v2 offset:2240
	v_mul_f32_e32 v2, v41, v89
	v_cvt_pk_bf16_f32 v2, v2, v183
	ds_write_b16 v18, v2 offset:2304
	v_mul_f32_e32 v2, v25, v89
	v_cvt_pk_bf16_f32 v2, v2, v183
	v_ashrrev_i32_e32 v77, 31, v76
	ds_write_b16 v18, v2 offset:2368
	v_lshlrev_b64 v[2:3], 11, v[76:77]
	s_waitcnt lgkmcnt(0)
; __device__ __forceinline__ unsigned cvtpk(float lo, float hi) { unsigned r; asm volatile("v_cvt_pk_bf16_f32 %0, %1, %2" : "=v"(r) : "v"(lo), "v"(hi)); return r; }
; __device__ __forceinline__ void fox_block(const BlockRef& cur, const BlockRef& nxt, char* lds, char* cbcur, char* cbnxt, Seam& S) {
;     ...
;             asm volatile("s_waitcnt lgkmcnt(0)" ::: "memory");
; #pragma unroll
;             for (int it = 0; it < 4; ++it) { const int lrow = it * 4 + (ln >> 4), ch = ln & 15, grow = half * 16 + lrow;
;                 const u32x4 ov = *(const u32x4*)(stg + lrow * 272 + ch * 16); const u32x4 z = *(const u32x4*)(Zw + (size_t)grow * ZP + ch * 8);
;                 u32x4 w;
;                 w.x = cvtpk(__uint_as_float(ov.x << 16) * __uint_as_float(z.x << 16), __uint_as_float(ov.x & 0xffff0000u) * __uint_as_float(z.x & 0xffff0000u));
;                 w.y = cvtpk(__uint_as_float(ov.y << 16) * __uint_as_float(z.y << 16), __uint_as_float(ov.y & 0xffff0000u) * __uint_as_float(z.y & 0xffff0000u));
;                 w.z = cvtpk(__uint_as_float(ov.z << 16) * __uint_as_float(z.z << 16), __uint_as_float(ov.z & 0xffff0000u) * __uint_as_float(z.z & 0xffff0000u));
;                 w.w = cvtpk(__uint_as_float(ov.w << 16) * __uint_as_float(z.w << 16), __uint_as_float(ov.w & 0xffff0000u) * __uint_as_float(z.w & 0xffff0000u));
;                 *(u32x4*)(Ow + (size_t)grow * QP + ch * 8) = w; }
	v_lshl_add_u64 v[2:3], v[74:75], 0, v[2:3]
	v_mul_lo_u32 v2, v76, s80
	v_add3_u32 v4, s69, v82, v2
	ds_read_b128 v[20:23], v4
	v_lshl_add_u64 v[2:3], s[4:5], 0, v[82:83]
	v_add_u32_e32 v24, 4, v76
	v_ashrrev_i32_e32 v25, 31, v24
	v_add_u32_e32 v34, 8, v76
	s_waitcnt lgkmcnt(0)
	v_lshlrev_b32_e32 v5, 16, v20
	s_add_i32 s14, s68, 0x100
	v_cmp_gt_i32_e32 vcc, s14, v239
	s_waitcnt vmcnt(7)
	v_mov_b32_e32 v6, v166
	v_mov_b32_e32 v7, v167
	v_mov_b32_e32 v8, v168
	v_mov_b32_e32 v9, v169
	v_lshlrev_b32_e32 v19, 16, v6
	v_mul_f32_e32 v5, v19, v5
	v_and_b32_e32 v6, 0xffff0000, v6
	v_and_b32_e32 v19, 0xffff0000, v20
	v_mul_f32_e32 v6, v6, v19
	v_cvt_pk_bf16_f32 v6, v5, v6
	v_lshlrev_b32_e32 v5, 16, v21
	v_lshlrev_b32_e32 v19, 16, v7
	v_mul_f32_e32 v5, v19, v5
	v_and_b32_e32 v7, 0xffff0000, v7
	v_and_b32_e32 v19, 0xffff0000, v21
	v_mul_f32_e32 v7, v7, v19
	v_cvt_pk_bf16_f32 v7, v5, v7
	v_lshlrev_b32_e32 v5, 16, v22
	v_lshlrev_b32_e32 v19, 16, v8
	v_mul_f32_e32 v5, v19, v5
	v_and_b32_e32 v8, 0xffff0000, v8
	v_and_b32_e32 v19, 0xffff0000, v22
	v_mul_f32_e32 v8, v8, v19
	v_cvt_pk_bf16_f32 v8, v5, v8
	v_lshlrev_b32_e32 v5, 16, v23
	v_lshlrev_b32_e32 v19, 16, v9
	v_mul_f32_e32 v5, v19, v5
	v_and_b32_e32 v9, 0xffff0000, v9
	v_and_b32_e32 v19, 0xffff0000, v23
	v_lshlrev_b64 v[20:21], 12, v[76:77]
	v_mul_f32_e32 v9, v9, v19
	v_lshl_add_u64 v[20:21], v[2:3], 0, v[20:21]
	v_cvt_pk_bf16_f32 v9, v5, v9
	global_store_dwordx4 v[20:21], v[6:9], off
	ds_read_b128 v[20:23], v4 offset:1088
	s_waitcnt lgkmcnt(0)
	v_lshlrev_b32_e32 v5, 16, v20
	v_lshlrev_b64 v[6:7], 11, v[24:25]
	v_lshl_add_u64 v[6:7], v[74:75], 0, v[6:7]
	v_and_b32_e32 v19, 0xffff0000, v20
	v_lshlrev_b32_e32 v20, 16, v21
	v_and_b32_e32 v21, 0xffff0000, v21
	v_lshlrev_b64 v[24:25], 12, v[24:25]
	v_lshlrev_b32_e32 v35, 16, v22
	v_and_b32_e32 v22, 0xffff0000, v22
	v_lshlrev_b32_e32 v36, 16, v23
	v_and_b32_e32 v23, 0xffff0000, v23
	v_lshl_add_u64 v[24:25], v[2:3], 0, v[24:25]
	s_waitcnt vmcnt(7)
	v_mov_b32_e32 v6, v170
	v_mov_b32_e32 v7, v171
	v_mov_b32_e32 v8, v172
	v_mov_b32_e32 v9, v173
	v_lshlrev_b32_e32 v37, 16, v6
	v_and_b32_e32 v6, 0xffff0000, v6
	v_lshlrev_b32_e32 v38, 16, v7
	v_and_b32_e32 v7, 0xffff0000, v7
	v_lshlrev_b32_e32 v39, 16, v8
	v_and_b32_e32 v8, 0xffff0000, v8
	v_lshlrev_b32_e32 v40, 16, v9
	v_and_b32_e32 v9, 0xffff0000, v9
	v_mul_f32_e32 v6, v6, v19
	v_mul_f32_e32 v7, v7, v21
	v_mul_f32_e32 v5, v37, v5
	v_mul_f32_e32 v19, v38, v20
	v_mul_f32_e32 v20, v39, v35
	v_mul_f32_e32 v8, v8, v22
	v_mul_f32_e32 v9, v9, v23
	v_cvt_pk_bf16_f32 v6, v5, v6
	v_cvt_pk_bf16_f32 v7, v19, v7
	v_ashrrev_i32_e32 v35, 31, v34
	v_mul_f32_e32 v21, v40, v36
	v_cvt_pk_bf16_f32 v8, v20, v8
	v_cvt_pk_bf16_f32 v9, v21, v9
	global_store_dwordx4 v[24:25], v[6:9], off
	ds_read_b128 v[20:23], v4 offset:2176
	v_add_u32_e32 v24, 12, v76
	v_lshlrev_b64 v[6:7], 11, v[34:35]
	v_lshl_add_u64 v[6:7], v[74:75], 0, v[6:7]
	v_ashrrev_i32_e32 v25, 31, v24
	v_lshlrev_b64 v[34:35], 12, v[34:35]
	s_waitcnt lgkmcnt(0)
	v_lshlrev_b32_e32 v5, 16, v20
	v_and_b32_e32 v19, 0xffff0000, v20
	v_lshlrev_b32_e32 v20, 16, v21
	v_and_b32_e32 v21, 0xffff0000, v21
	v_lshlrev_b32_e32 v38, 16, v22
	v_and_b32_e32 v22, 0xffff0000, v22
	v_lshlrev_b32_e32 v39, 16, v23
	v_and_b32_e32 v23, 0xffff0000, v23
	v_lshlrev_b64 v[36:37], 11, v[24:25]
	v_lshl_add_u64 v[34:35], v[2:3], 0, v[34:35]
	v_lshl_add_u64 v[36:37], v[74:75], 0, v[36:37]
	s_waitcnt vmcnt(7)
	v_mov_b32_e32 v6, v174
	v_mov_b32_e32 v7, v175
	v_mov_b32_e32 v8, v176
	v_mov_b32_e32 v9, v177
	v_lshlrev_b32_e32 v40, 16, v6
	v_and_b32_e32 v6, 0xffff0000, v6
	v_lshlrev_b32_e32 v41, 16, v7
	v_and_b32_e32 v7, 0xffff0000, v7
	v_lshlrev_b32_e32 v50, 16, v8
	v_and_b32_e32 v8, 0xffff0000, v8
	v_lshlrev_b32_e32 v51, 16, v9
	v_and_b32_e32 v9, 0xffff0000, v9
	v_mul_f32_e32 v6, v6, v19
	v_mul_f32_e32 v7, v7, v21
	v_mul_f32_e32 v8, v8, v22
	v_mul_f32_e32 v9, v9, v23
	v_mul_f32_e32 v5, v40, v5
	v_mul_f32_e32 v19, v41, v20
	v_mul_f32_e32 v20, v50, v38
	v_mul_f32_e32 v21, v51, v39
	v_cvt_pk_bf16_f32 v6, v5, v6
	v_cvt_pk_bf16_f32 v7, v19, v7
	v_cvt_pk_bf16_f32 v8, v20, v8
	v_cvt_pk_bf16_f32 v9, v21, v9
	global_store_dwordx4 v[34:35], v[6:9], off
	v_rcp_f32_e32 v5, v66
	v_rcp_f32_e32 v19, v67
	v_rcp_f32_e32 v34, v68
	v_rcp_f32_e32 v35, v69
	v_mul_f32_e32 v40, v10, v5
	v_mul_f32_e32 v41, v58, v5
	v_mul_f32_e32 v42, v42, v5
	v_mul_f32_e32 v5, v26, v5
	v_mul_f32_e32 v26, v11, v19
	v_mul_f32_e32 v50, v59, v19
	v_mul_f32_e32 v43, v43, v19
	v_mul_f32_e32 v19, v27, v19
	v_mul_f32_e32 v27, v12, v34
	v_mul_f32_e32 v51, v60, v34
	v_mul_f32_e32 v44, v44, v34
	v_mul_f32_e32 v28, v28, v34
	v_mul_f32_e32 v34, v13, v35
	ds_read_b128 v[10:13], v4 offset:3264
	v_rcp_f32_e32 v36, v70
	v_rcp_f32_e32 v37, v71
	v_rcp_f32_e32 v38, v72
	v_rcp_f32_e32 v39, v73
	v_lshlrev_b64 v[22:23], 12, v[24:25]
	v_mul_f32_e32 v52, v61, v35
	v_mul_f32_e32 v45, v45, v35
	v_mul_f32_e32 v29, v29, v35
	v_mul_f32_e32 v14, v14, v36
	v_mul_f32_e32 v35, v62, v36
	v_mul_f32_e32 v46, v46, v36
	v_mul_f32_e32 v30, v30, v36
	v_mul_f32_e32 v15, v15, v37
	v_mul_f32_e32 v36, v63, v37
	v_mul_f32_e32 v47, v47, v37
	v_mul_f32_e32 v31, v31, v37
	v_mul_f32_e32 v16, v16, v38
	v_mul_f32_e32 v37, v64, v38
	v_mul_f32_e32 v48, v48, v38
	v_mul_f32_e32 v32, v32, v38
	v_mul_f32_e32 v17, v17, v39
	v_mul_f32_e32 v38, v65, v39
	v_mul_f32_e32 v49, v49, v39
	v_mul_f32_e32 v33, v33, v39
	s_waitcnt lgkmcnt(0)
	v_lshlrev_b32_e32 v39, 16, v10
	v_and_b32_e32 v10, 0xffff0000, v10
	v_lshlrev_b32_e32 v53, 16, v11
	v_and_b32_e32 v11, 0xffff0000, v11
	v_lshlrev_b32_e32 v54, 16, v12
	v_and_b32_e32 v12, 0xffff0000, v12
	v_lshlrev_b32_e32 v55, 16, v13
	v_and_b32_e32 v13, 0xffff0000, v13
	v_lshl_add_u64 v[22:23], v[2:3], 0, v[22:23]
	v_add_u32_e32 v20, 16, v76
	v_ashrrev_i32_e32 v21, 31, v20
	v_lshlrev_b64 v[24:25], 11, v[20:21]
	v_lshl_add_u64 v[24:25], v[74:75], 0, v[24:25]
	s_waitcnt vmcnt(7)
; __device__ __forceinline__ unsigned cvtpk(float lo, float hi) { unsigned r; asm volatile("v_cvt_pk_bf16_f32 %0, %1, %2" : "=v"(r) : "v"(lo), "v"(hi)); return r; }
; __device__ __forceinline__ void fox_block(const BlockRef& cur, const BlockRef& nxt, char* lds, char* cbcur, char* cbnxt, Seam& S) {
;     ...
; #pragma unroll
;         for (int half = 0; half < 2; ++half) {
; #pragma unroll
;             for (int rr = 0; rr < 8; ++rr) { const int r = half * 8 + rr; const int lrow = (rr & 3) + 8 * (rr >> 2) + 4 * hie;
; #pragma unroll
;                 for (int d0 = 0; d0 < 4; ++d0) *(unsigned short*)(stg + lrow * 272 + (d0 * 32 + r32e) * 2) = (unsigned short)cvtpk(o[d0][r] * rli[r], 0.f); }
;             asm volatile("s_waitcnt lgkmcnt(0)" ::: "memory");
; #pragma unroll
;             for (int it = 0; it < 4; ++it) { const int lrow = it * 4 + (ln >> 4), ch = ln & 15, grow = half * 16 + lrow;
;                 const u32x4 ov = *(const u32x4*)(stg + lrow * 272 + ch * 16); const u32x4 z = *(const u32x4*)(Zw + (size_t)grow * ZP + ch * 8);
;                 u32x4 w;
;                 w.x = cvtpk(__uint_as_float(ov.x << 16) * __uint_as_float(z.x << 16), __uint_as_float(ov.x & 0xffff0000u) * __uint_as_float(z.x & 0xffff0000u));
;                 w.y = cvtpk(__uint_as_float(ov.y << 16) * __uint_as_float(z.y << 16), __uint_as_float(ov.y & 0xffff0000u) * __uint_as_float(z.y & 0xffff0000u));
;                 w.z = cvtpk(__uint_as_float(ov.z << 16) * __uint_as_float(z.z << 16), __uint_as_float(ov.z & 0xffff0000u) * __uint_as_float(z.z & 0xffff0000u));
;                 w.w = cvtpk(__uint_as_float(ov.w << 16) * __uint_as_float(z.w << 16), __uint_as_float(ov.w & 0xffff0000u) * __uint_as_float(z.w & 0xffff0000u));
;                 *(u32x4*)(Ow + (size_t)grow * QP + ch * 8) = w; }
;             asm volatile("s_waitcnt lgkmcnt(0)" ::: "memory");
;         }
	v_mov_b32_e32 v6, v178
	v_mov_b32_e32 v7, v179
	v_mov_b32_e32 v8, v180
	v_mov_b32_e32 v9, v181
	v_lshlrev_b32_e32 v56, 16, v6
	v_and_b32_e32 v6, 0xffff0000, v6
	v_lshlrev_b32_e32 v57, 16, v7
	v_and_b32_e32 v7, 0xffff0000, v7
	v_lshlrev_b32_e32 v58, 16, v8
	v_and_b32_e32 v8, 0xffff0000, v8
	v_lshlrev_b32_e32 v59, 16, v9
	v_and_b32_e32 v9, 0xffff0000, v9
	v_mul_f32_e32 v6, v6, v10
	v_mul_f32_e32 v7, v7, v11
	v_mul_f32_e32 v8, v8, v12
	v_mul_f32_e32 v9, v9, v13
	v_mul_f32_e32 v39, v56, v39
	v_mul_f32_e32 v10, v57, v53
	v_mul_f32_e32 v11, v58, v54
	v_mul_f32_e32 v12, v59, v55
	v_cvt_pk_bf16_f32 v6, v39, v6
	v_cvt_pk_bf16_f32 v7, v10, v7
	v_cvt_pk_bf16_f32 v8, v11, v8
	v_cvt_pk_bf16_f32 v9, v12, v9
	global_store_dwordx4 v[22:23], v[6:9], off
	s_waitcnt lgkmcnt(0)
	s_nop 1
	v_cvt_pk_bf16_f32 v6, v40, v183
	ds_write_b16 v78, v6
	v_cvt_pk_bf16_f32 v6, v41, v183
	ds_write_b16 v78, v6 offset:64
	v_cvt_pk_bf16_f32 v6, v42, v183
	ds_write_b16 v78, v6 offset:128
	v_cvt_pk_bf16_f32 v5, v5, v183
	ds_write_b16 v78, v5 offset:192
	v_cvt_pk_bf16_f32 v5, v26, v183
	ds_write_b16 v78, v5 offset:272
	v_cvt_pk_bf16_f32 v5, v50, v183
	ds_write_b16 v78, v5 offset:336
	v_cvt_pk_bf16_f32 v5, v43, v183
	ds_write_b16 v78, v5 offset:400
	v_cvt_pk_bf16_f32 v5, v19, v183
	ds_write_b16 v78, v5 offset:464
	v_cvt_pk_bf16_f32 v5, v27, v183
	ds_write_b16 v78, v5 offset:544
	v_cvt_pk_bf16_f32 v5, v51, v183
	ds_write_b16 v78, v5 offset:608
	v_cvt_pk_bf16_f32 v5, v44, v183
	ds_write_b16 v78, v5 offset:672
	v_cvt_pk_bf16_f32 v5, v28, v183
	ds_write_b16 v78, v5 offset:736
	v_cvt_pk_bf16_f32 v5, v34, v183
	ds_write_b16 v18, v5
	v_cvt_pk_bf16_f32 v5, v52, v183
	ds_write_b16 v18, v5 offset:64
	v_cvt_pk_bf16_f32 v5, v45, v183
	ds_write_b16 v18, v5 offset:128
	v_cvt_pk_bf16_f32 v5, v29, v183
	ds_write_b16 v18, v5 offset:192
	v_cvt_pk_bf16_f32 v5, v14, v183
	ds_write_b16 v78, v5 offset:2176
	v_cvt_pk_bf16_f32 v5, v35, v183
	ds_write_b16 v78, v5 offset:2240
	v_cvt_pk_bf16_f32 v5, v46, v183
	ds_write_b16 v78, v5 offset:2304
	v_cvt_pk_bf16_f32 v5, v30, v183
	ds_write_b16 v78, v5 offset:2368
	v_cvt_pk_bf16_f32 v5, v15, v183
	ds_write_b16 v78, v5 offset:2448
	v_cvt_pk_bf16_f32 v5, v36, v183
	ds_write_b16 v78, v5 offset:2512
	v_cvt_pk_bf16_f32 v5, v47, v183
	ds_write_b16 v78, v5 offset:2576
	v_cvt_pk_bf16_f32 v5, v31, v183
	ds_write_b16 v78, v5 offset:2640
	v_cvt_pk_bf16_f32 v5, v16, v183
	ds_write_b16 v78, v5 offset:2720
	v_cvt_pk_bf16_f32 v5, v37, v183
	ds_write_b16 v78, v5 offset:2784
	v_cvt_pk_bf16_f32 v5, v48, v183
	ds_write_b16 v78, v5 offset:2848
	v_cvt_pk_bf16_f32 v5, v32, v183
	ds_write_b16 v78, v5 offset:2912
	v_cvt_pk_bf16_f32 v5, v17, v183
	ds_write_b16 v18, v5 offset:2176
	v_cvt_pk_bf16_f32 v5, v38, v183
	ds_write_b16 v18, v5 offset:2240
	v_cvt_pk_bf16_f32 v5, v49, v183
	ds_write_b16 v18, v5 offset:2304
	v_cvt_pk_bf16_f32 v5, v33, v183
	ds_write_b16 v18, v5 offset:2368
	s_waitcnt lgkmcnt(0)
	ds_read_b128 v[10:13], v4
	v_add_u32_e32 v14, 20, v76
	v_ashrrev_i32_e32 v15, 31, v14
	v_lshlrev_b64 v[16:17], 12, v[20:21]
	v_lshlrev_b64 v[18:19], 11, v[14:15]
	s_waitcnt lgkmcnt(0)
	v_lshlrev_b32_e32 v5, 16, v10
	v_and_b32_e32 v10, 0xffff0000, v10
	v_lshlrev_b32_e32 v20, 16, v11
	v_and_b32_e32 v11, 0xffff0000, v11
	v_lshlrev_b32_e32 v21, 16, v12
	v_and_b32_e32 v12, 0xffff0000, v12
	v_lshlrev_b32_e32 v22, 16, v13
	v_and_b32_e32 v13, 0xffff0000, v13
	v_lshl_add_u64 v[16:17], v[2:3], 0, v[16:17]
	v_lshl_add_u64 v[18:19], v[74:75], 0, v[18:19]
	v_lshlrev_b64 v[14:15], 12, v[14:15]
	v_lshl_add_u64 v[14:15], v[2:3], 0, v[14:15]
	s_waitcnt vmcnt(7)
	v_mov_b32_e32 v6, v240
	v_mov_b32_e32 v7, v241
	v_mov_b32_e32 v8, v242
	v_mov_b32_e32 v9, v243
	v_lshlrev_b32_e32 v23, 16, v6
	v_and_b32_e32 v6, 0xffff0000, v6
	v_lshlrev_b32_e32 v24, 16, v7
	v_and_b32_e32 v7, 0xffff0000, v7
	v_lshlrev_b32_e32 v25, 16, v8
	v_and_b32_e32 v8, 0xffff0000, v8
	v_lshlrev_b32_e32 v26, 16, v9
	v_and_b32_e32 v9, 0xffff0000, v9
	v_mul_f32_e32 v6, v6, v10
	v_mul_f32_e32 v7, v7, v11
	v_mul_f32_e32 v8, v8, v12
	v_mul_f32_e32 v9, v9, v13
	v_mul_f32_e32 v5, v23, v5
	v_mul_f32_e32 v10, v24, v20
	v_mul_f32_e32 v11, v25, v21
	v_mul_f32_e32 v12, v26, v22
	v_cvt_pk_bf16_f32 v6, v5, v6
	v_cvt_pk_bf16_f32 v7, v10, v7
	v_cvt_pk_bf16_f32 v8, v11, v8
	v_cvt_pk_bf16_f32 v9, v12, v9
	global_store_dwordx4 v[16:17], v[6:9], off
	ds_read_b128 v[10:13], v4 offset:1088
	v_add_u32_e32 v16, 24, v76
	v_ashrrev_i32_e32 v17, 31, v16
	v_lshlrev_b64 v[18:19], 11, v[16:17]
	v_lshl_add_u64 v[18:19], v[74:75], 0, v[18:19]
	s_waitcnt lgkmcnt(0)
; __device__ __forceinline__ unsigned cvtpk(float lo, float hi) { unsigned r; asm volatile("v_cvt_pk_bf16_f32 %0, %1, %2" : "=v"(r) : "v"(lo), "v"(hi)); return r; }
; __device__ __forceinline__ void fill_cb(const float* C, int P0, char* cb) {
;     const int n = P0 + QB; const float ref = C[P0];
;     for (int i = threadIdx.x * 4; i < n; i += 2048) { const f32x4 c = *(const f32x4*)(C + i); u32x4 o0, o1;
; #pragma unroll
;         for (int j = 0; j < 4; ++j) { const float x = (ref - c[j]) * INV_SCALE; const unsigned u1 = __float_as_uint(x) & 0xffff0000u; const float r1 = x - __uint_as_float(u1);
;             const unsigned u2 = __float_as_uint(r1) & 0xffff0000u; const float r2 = r1 - __uint_as_float(u2); const unsigned u3 = cvtpk(r2, 0.f) & 0xffffu;
;             const unsigned w0 = (u1 >> 16) | u2, w1 = u3;
;             if (j < 2) { o0[2 * j] = w0; o0[2 * j + 1] = w1; } else { o1[2 * (j - 2)] = w0; o1[2 * (j - 2) + 1] = w1; } }
;         *(u32x4*)(cb + (size_t)i * 8) = o0; *(u32x4*)(cb + (size_t)i * 8 + 16) = o1; }
; }
; __device__ __forceinline__ void fox_block(const BlockRef& cur, const BlockRef& nxt, char* lds, char* cbcur, char* cbnxt, Seam& S) {
;     ...
;             for (int it = 0; it < 4; ++it) { const int lrow = it * 4 + (ln >> 4), ch = ln & 15, grow = half * 16 + lrow;
;                 const u32x4 ov = *(const u32x4*)(stg + lrow * 272 + ch * 16); const u32x4 z = *(const u32x4*)(Zw + (size_t)grow * ZP + ch * 8);
;                 u32x4 w;
;                 w.x = cvtpk(__uint_as_float(ov.x << 16) * __uint_as_float(z.x << 16), __uint_as_float(ov.x & 0xffff0000u) * __uint_as_float(z.x & 0xffff0000u));
;                 w.y = cvtpk(__uint_as_float(ov.y << 16) * __uint_as_float(z.y << 16), __uint_as_float(ov.y & 0xffff0000u) * __uint_as_float(z.y & 0xffff0000u));
;                 w.z = cvtpk(__uint_as_float(ov.z << 16) * __uint_as_float(z.z << 16), __uint_as_float(ov.z & 0xffff0000u) * __uint_as_float(z.z & 0xffff0000u));
;                 w.w = cvtpk(__uint_as_float(ov.w << 16) * __uint_as_float(z.w << 16), __uint_as_float(ov.w & 0xffff0000u) * __uint_as_float(z.w & 0xffff0000u));
;                 *(u32x4*)(Ow + (size_t)grow * QP + ch * 8) = w; }
	v_lshlrev_b32_e32 v5, 16, v10
	v_and_b32_e32 v10, 0xffff0000, v10
	v_lshlrev_b32_e32 v20, 16, v11
	v_and_b32_e32 v11, 0xffff0000, v11
	v_lshlrev_b32_e32 v21, 16, v12
	v_and_b32_e32 v12, 0xffff0000, v12
	v_lshlrev_b32_e32 v22, 16, v13
	v_and_b32_e32 v13, 0xffff0000, v13
	v_lshlrev_b64 v[16:17], 12, v[16:17]
	v_lshl_add_u64 v[16:17], v[2:3], 0, v[16:17]
	s_waitcnt vmcnt(7)
	v_mov_b32_e32 v6, v244
	v_mov_b32_e32 v7, v245
	v_mov_b32_e32 v8, v246
	v_mov_b32_e32 v9, v247
	v_lshlrev_b32_e32 v23, 16, v6
	v_and_b32_e32 v6, 0xffff0000, v6
	v_lshlrev_b32_e32 v24, 16, v7
	v_and_b32_e32 v7, 0xffff0000, v7
	v_lshlrev_b32_e32 v25, 16, v8
	v_and_b32_e32 v8, 0xffff0000, v8
	v_lshlrev_b32_e32 v26, 16, v9
	v_and_b32_e32 v9, 0xffff0000, v9
	v_mul_f32_e32 v6, v6, v10
	v_mul_f32_e32 v7, v7, v11
	v_mul_f32_e32 v8, v8, v12
	v_mul_f32_e32 v9, v9, v13
	v_mul_f32_e32 v5, v23, v5
	v_mul_f32_e32 v10, v24, v20
	v_mul_f32_e32 v11, v25, v21
	v_mul_f32_e32 v12, v26, v22
	v_cvt_pk_bf16_f32 v6, v5, v6
	v_cvt_pk_bf16_f32 v7, v10, v7
	v_cvt_pk_bf16_f32 v8, v11, v8
	v_cvt_pk_bf16_f32 v9, v12, v9
	global_store_dwordx4 v[14:15], v[6:9], off
	ds_read_b128 v[10:13], v4 offset:2176
	v_add_u32_e32 v14, 28, v76
	v_ashrrev_i32_e32 v15, 31, v14
	v_lshlrev_b64 v[18:19], 11, v[14:15]
	v_lshl_add_u64 v[18:19], v[74:75], 0, v[18:19]
	s_waitcnt lgkmcnt(0)
	v_lshlrev_b32_e32 v5, 16, v10
	v_and_b32_e32 v10, 0xffff0000, v10
	v_lshlrev_b32_e32 v20, 16, v11
	v_and_b32_e32 v11, 0xffff0000, v11
	v_lshlrev_b32_e32 v21, 16, v12
	v_and_b32_e32 v12, 0xffff0000, v12
	v_lshlrev_b32_e32 v22, 16, v13
	v_and_b32_e32 v13, 0xffff0000, v13
	v_lshlrev_b64 v[14:15], 12, v[14:15]
	v_lshl_add_u64 v[2:3], v[2:3], 0, v[14:15]
	s_waitcnt vmcnt(7)
	v_mov_b32_e32 v6, v248
	v_mov_b32_e32 v7, v249
	v_mov_b32_e32 v8, v250
	v_mov_b32_e32 v9, v251
	v_lshlrev_b32_e32 v23, 16, v6
	v_and_b32_e32 v6, 0xffff0000, v6
	v_lshlrev_b32_e32 v24, 16, v7
	v_and_b32_e32 v7, 0xffff0000, v7
	v_lshlrev_b32_e32 v25, 16, v8
	v_and_b32_e32 v8, 0xffff0000, v8
	v_lshlrev_b32_e32 v26, 16, v9
	v_and_b32_e32 v9, 0xffff0000, v9
	v_mul_f32_e32 v6, v6, v10
	v_mul_f32_e32 v7, v7, v11
	v_mul_f32_e32 v8, v8, v12
	v_mul_f32_e32 v9, v9, v13
	v_mul_f32_e32 v5, v23, v5
	v_mul_f32_e32 v10, v24, v20
	v_mul_f32_e32 v11, v25, v21
	v_mul_f32_e32 v12, v26, v22
	v_cvt_pk_bf16_f32 v6, v5, v6
	v_cvt_pk_bf16_f32 v7, v10, v7
	v_cvt_pk_bf16_f32 v8, v11, v8
	v_cvt_pk_bf16_f32 v9, v12, v9
	global_store_dwordx4 v[16:17], v[6:9], off
	ds_read_b128 v[10:13], v4 offset:3264
	s_waitcnt lgkmcnt(0)
	v_lshlrev_b32_e32 v4, 16, v10
	v_and_b32_e32 v5, 0xffff0000, v10
	v_lshlrev_b32_e32 v10, 16, v11
	v_and_b32_e32 v11, 0xffff0000, v11
	v_lshlrev_b32_e32 v16, 16, v12
	v_and_b32_e32 v12, 0xffff0000, v12
	v_lshlrev_b32_e32 v17, 16, v13
	v_and_b32_e32 v13, 0xffff0000, v13
	s_waitcnt vmcnt(7)
	v_mov_b32_e32 v6, v252
	v_mov_b32_e32 v7, v253
	v_mov_b32_e32 v8, v254
	v_mov_b32_e32 v9, v255
	v_lshlrev_b32_e32 v18, 16, v6
	v_and_b32_e32 v6, 0xffff0000, v6
	v_lshlrev_b32_e32 v19, 16, v7
	v_and_b32_e32 v7, 0xffff0000, v7
	v_lshlrev_b32_e32 v20, 16, v8
	v_and_b32_e32 v8, 0xffff0000, v8
	v_lshlrev_b32_e32 v21, 16, v9
	v_and_b32_e32 v9, 0xffff0000, v9
	v_mul_f32_e32 v4, v18, v4
	v_mul_f32_e32 v5, v6, v5
	v_mul_f32_e32 v6, v19, v10
	v_mul_f32_e32 v7, v7, v11
	v_mul_f32_e32 v10, v20, v16
	v_mul_f32_e32 v8, v8, v12
	v_mul_f32_e32 v11, v21, v17
	v_mul_f32_e32 v9, v9, v13
	v_cvt_pk_bf16_f32 v4, v4, v5
	v_cvt_pk_bf16_f32 v5, v6, v7
	v_cvt_pk_bf16_f32 v6, v10, v8
	v_cvt_pk_bf16_f32 v7, v11, v9
	global_store_dwordx4 v[2:3], v[4:7], off
	s_waitcnt lgkmcnt(0)
	s_and_saveexec_b64 s[4:5], vcc
	s_cbranch_execz .LBB0_224
	s_mov_b32 s69, s15
	s_lshl_b64 s[70:71], s[68:69], 2
	s_add_u32 s70, s12, s70
	s_addc_u32 s71, s13, s71
	global_load_dword v4, v183, s[70:71]
	v_lshl_add_u64 v[2:3], s[12:13], 0, v[184:185]
	s_mov_b64 s[70:71], 0
	v_add_u32_e32 v5, 0x10800, v184
	v_mov_b32_e32 v6, v239
.LBB0_262:
	global_load_dwordx4 v[8:11], v[2:3], off
	v_add_u32_e32 v6, 0x800, v6
	v_cmp_le_i32_e32 vcc, s14, v6
	v_lshl_add_u64 v[2:3], v[2:3], 0, s[18:19]
	s_or_b64 s[70:71], vcc, s[70:71]
	s_waitcnt vmcnt(0)
	v_sub_f32_e32 v8, v4, v8
	v_sub_f32_e32 v9, v4, v9
	v_sub_f32_e32 v10, v4, v10
	v_sub_f32_e32 v11, v4, v11
	v_mul_f32_e32 v12, 0x413504f3, v8
	v_mul_f32_e32 v13, 0x413504f3, v9
	v_mul_f32_e32 v14, 0x413504f3, v10
	v_mul_f32_e32 v15, 0x413504f3, v11
	ds_write_b128 v5, v[12:15]
	v_add_u32_e32 v5, 0x2000, v5
	s_andn2_b64 exec, exec, s[70:71]
	s_cbranch_execnz .LBB0_262
	s_branch .LBB0_224
